# GEMM tile prologue (phase A / C): no full vmcnt drain of the previous tile's epilogue stores before the first barrier; they drain under the first K-tiles' DMA
# baseline (speedup 1.0000x reference)
.LBB0_94:
	s_ashr_i32 s0, s2, 31
	s_lshr_b32 s0, s0, 29
	s_add_i32 s0, s2, s0
	v_mov_b32_e32 v78, v133
	s_and_b32 s1, s0, 0x1fffff8
	s_lshl_b32 s0, s0, 5
	s_and_b32 s22, s0, 0xffffff00
	v_ashrrev_i32_e32 v6, 6, v78
	v_bfe_u32 v7, v78, 3, 3
	v_lshl_or_b32 v8, v6, 5, v7
	v_add_u32_e32 v0, s22, v8
	s_waitcnt lgkmcnt(0)
	v_ashrrev_i32_e32 v1, 31, v0
	v_lshlrev_b64 v[2:3], 11, v[0:1]
	v_bfe_u32 v1, v78, 4, 2
	v_readlane_b32 s20, v214, 4
	v_xor_b32_e32 v1, v1, v78
	v_readlane_b32 s21, v214, 5
	v_lshlrev_b32_e32 v1, 4, v1
	v_and_b32_e32 v64, 0x70, v1
	v_lshl_add_u64 v[2:3], s[20:21], 0, v[2:3]
	v_or_b32_e32 v1, 8, v8
	v_lshl_add_u64 v[66:67], v[2:3], 0, v[64:65]
	v_add_u32_e32 v2, s22, v1
	v_lshrrev_b32_e32 v1, 1, v1
	v_xor_b32_e32 v1, v1, v78
	v_ashrrev_i32_e32 v3, 31, v2
	v_lshlrev_b32_e32 v1, 4, v1
	v_or_b32_e32 v0, 16, v0
	v_lshlrev_b64 v[2:3], 11, v[2:3]
	v_and_b32_e32 v4, 0x70, v1
	v_ashrrev_i32_e32 v1, 31, v0
	v_lshl_add_u64 v[2:3], s[20:21], 0, v[2:3]
	v_mov_b32_e32 v5, v65
	v_lshlrev_b64 v[0:1], 11, v[0:1]
	v_lshl_add_u64 v[68:69], v[2:3], 0, v[4:5]
	v_lshl_add_u64 v[0:1], s[20:21], 0, v[0:1]
	v_or_b32_e32 v2, 24, v8
	v_lshl_add_u64 v[70:71], v[0:1], 0, v[64:65]
	v_add_u32_e32 v0, s22, v2
	v_lshrrev_b32_e32 v2, 1, v2
	v_ashrrev_i32_e32 v1, 31, v0
	v_xor_b32_e32 v2, v2, v78
	v_lshlrev_b64 v[0:1], 11, v[0:1]
	v_lshlrev_b32_e32 v2, 4, v2
	s_sub_i32 s1, s2, s1
	v_lshl_add_u64 v[0:1], s[20:21], 0, v[0:1]
	v_and_b32_e32 v2, 0x70, v2
	v_mov_b32_e32 v3, v65
	s_lshl_b32 s0, s1, 7
	v_lshl_add_u64 v[72:73], v[0:1], 0, v[2:3]
	v_lshl_or_b32 v2, v6, 4, v7
	v_add_u32_e32 v0, s0, v2
	v_lshlrev_b32_e32 v3, 12, v6
	v_ashrrev_i32_e32 v1, 31, v0
	v_add_u32_e32 v126, 0, v3
	v_lshlrev_b64 v[0:1], 11, v[0:1]
	s_nop 0
	v_readfirstlane_b32 s38, v126
	v_add_u32_e32 v127, 0x400, v126
	v_lshl_add_u64 v[0:1], s[40:41], 0, v[0:1]
	v_or_b32_e32 v2, 8, v2
	s_waitcnt lgkmcnt(0)
	s_barrier
	s_mov_b32 m0, s38
	v_readfirstlane_b32 s39, v127
	v_add_u32_e32 v128, 0x800, v126
	v_lshlrev_b32_e32 v5, 11, v6
	v_and_b32_e32 v80, 1, v6
	v_lshl_add_u64 v[74:75], v[0:1], 0, v[64:65]
	v_add_u32_e32 v0, s0, v2
	v_lshrrev_b32_e32 v2, 1, v2
	global_load_lds_dwordx4 v[66:67], off
	s_mov_b32 m0, s39
	v_readfirstlane_b32 s48, v128
	v_add_u32_e32 v129, 0xc00, v126
	v_add_u32_e32 v6, 0, v5
	v_ashrrev_i32_e32 v1, 31, v0
	v_xor_b32_e32 v2, v2, v78
	global_load_lds_dwordx4 v[68:69], off
	s_mov_b32 m0, s48
	v_readfirstlane_b32 s49, v129
	v_add_u32_e32 v131, 0x8000, v6
	v_lshlrev_b64 v[0:1], 11, v[0:1]
	v_lshlrev_b32_e32 v2, 4, v2
	global_load_lds_dwordx4 v[70:71], off
	s_mov_b32 m0, s49
	v_readfirstlane_b32 s53, v131
	v_add_u32_e32 v130, 0x8400, v6
	v_lshl_add_u64 v[0:1], s[40:41], 0, v[0:1]
	v_and_b32_e32 v64, 0x70, v2
	global_load_lds_dwordx4 v[72:73], off
	s_mov_b32 m0, s53
	v_readfirstlane_b32 s54, v130
	v_add_u32_e32 v120, 0xc000, v126
	v_lshl_add_u64 v[76:77], v[0:1], 0, v[64:65]
	global_load_lds_dwordx4 v[74:75], off
	s_mov_b32 m0, s54
	s_mov_b64 s[20:21], 0x80
	v_readfirstlane_b32 s29, v120
	v_add_u32_e32 v121, 0xc400, v126
	global_load_lds_dwordx4 v[76:77], off
	v_lshl_add_u64 v[0:1], v[66:67], 0, s[20:21]
	s_mov_b32 m0, s29
	v_readfirstlane_b32 s33, v121
	v_add_u32_e32 v122, 0xc800, v126
	global_load_lds_dwordx4 v[0:1], off
	v_lshl_add_u64 v[0:1], v[68:69], 0, s[20:21]
	s_mov_b32 m0, s33
	v_readfirstlane_b32 s34, v122
	v_add_u32_e32 v123, 0xcc00, v126
	global_load_lds_dwordx4 v[0:1], off
	v_lshl_add_u64 v[0:1], v[70:71], 0, s[20:21]
	s_mov_b32 m0, s34
	v_readfirstlane_b32 s35, v123
	v_add_u32_e32 v124, s85, v5
	global_load_lds_dwordx4 v[0:1], off
	v_lshl_add_u64 v[0:1], v[72:73], 0, s[20:21]
	s_mov_b32 m0, s35
	v_readfirstlane_b32 s36, v124
	v_add_u32_e32 v125, 0x14400, v6
	global_load_lds_dwordx4 v[0:1], off
	v_lshl_add_u64 v[0:1], v[74:75], 0, s[20:21]
	s_mov_b32 m0, s36
	v_readfirstlane_b32 s37, v125
	global_load_lds_dwordx4 v[0:1], off
	v_lshl_add_u64 v[0:1], v[76:77], 0, s[20:21]
	s_mov_b32 m0, s37
	v_lshrrev_b32_e32 v2, 1, v78
	v_bfe_u32 v64, v78, 5, 1
	global_load_lds_dwordx4 v[0:1], off
	v_add_u32_e32 v114, s3, v3
	v_bitop3_b32 v0, v2, v64, 7 bitop3:0x6c
	s_waitcnt vmcnt(6)
	s_mov_b64 s[30:31], 0x100
	v_readfirstlane_b32 s1, v114
	v_add_u32_e32 v115, 0x400, v114
	v_lshlrev_b32_e32 v132, 4, v0
	s_waitcnt lgkmcnt(0)
	s_barrier
	v_lshl_add_u64 v[0:1], v[66:67], 0, s[30:31]
	s_mov_b32 m0, s1
	v_readfirstlane_b32 s20, v115
	v_add_u32_e32 v116, 0x800, v114
	global_load_lds_dwordx4 v[0:1], off
	v_lshl_add_u64 v[0:1], v[68:69], 0, s[30:31]
	s_mov_b32 m0, s20
	v_readfirstlane_b32 s21, v116
	v_add_u32_e32 v117, 0xc00, v114
	v_readlane_b32 s24, v212, 31
	v_and_b32_e32 v79, 31, v78
	global_load_lds_dwordx4 v[0:1], off
	v_lshl_add_u64 v[0:1], v[70:71], 0, s[30:31]
	s_mov_b32 m0, s21
	v_readfirstlane_b32 s23, v117
	v_add_u32_e32 v118, s24, v5
	v_add_u32_e32 v2, s3, v5
	v_lshlrev_b32_e32 v4, 7, v79
	global_load_lds_dwordx4 v[0:1], off
	v_lshl_add_u64 v[0:1], v[72:73], 0, s[30:31]
	s_mov_b32 m0, s23
	v_readfirstlane_b32 s24, v118
	v_add_u32_e32 v119, 0x8400, v2
	v_lshl_or_b32 v102, v80, 13, v4
	global_load_lds_dwordx4 v[0:1], off
	v_lshl_add_u64 v[0:1], v[74:75], 0, s[30:31]
	s_mov_b32 m0, s24
	v_readfirstlane_b32 s28, v119
	global_load_lds_dwordx4 v[0:1], off
	v_lshl_add_u64 v[0:1], v[76:77], 0, s[30:31]
	s_mov_b32 m0, s28
	v_add_u32_e32 v100, 0, v102
	global_load_lds_dwordx4 v[0:1], off
	v_add_u32_e32 v83, v100, v132
	v_ashrrev_i32_e32 v81, 7, v78
	ds_read_b128 a[0:3], v83 offset:32768
	ds_read_b128 a[4:7], v83 offset:36864
	v_lshl_or_b32 v134, v81, 13, v4
	v_add_u32_e32 v101, 0, v134
	v_add_u32_e32 v82, v101, v132
	ds_read_b128 a[8:11], v82
	ds_read_b128 a[12:15], v82 offset:4096
	v_lshrrev_b32_e32 v182, 6, v133
	s_nop 0
	v_readfirstlane_b32 s32, v182
	s_waitcnt lgkmcnt(1)
	v_mfma_f32_32x32x16_bf16 v[48:63], a[0:3], a[8:11], 0
	v_bfe_u32 v103, v78, 1, 3
	s_mov_b64 s[30:31], 0x180
	s_nop 0
	v_or_b32_e32 v143, 0x8000, v102
	v_or_b32_e32 v144, 0x9000, v102
	v_add_u32_e32 v145, s3, v134
	v_lshl_or_b32 v81, v81, 6, v79
	s_waitcnt vmcnt(12)
	v_mfma_f32_32x32x16_bf16 v[32:47], a[4:7], a[8:11], 0
	v_mul_lo_u32 v81, v81, s26
	s_mov_b64 s[80:81], 0x200
	s_waitcnt lgkmcnt(0)
	v_mfma_f32_32x32x16_bf16 v[16:31], a[0:3], a[12:15], 0
	v_bitop3_b32 v0, v64, v103, 2 bitop3:0x36
	v_lshlrev_b32_e32 v138, 4, v0
	v_add_u32_e32 v84, v101, v138
	ds_read_b128 a[28:31], v84 offset:4096
	s_nop 0
	s_nop 0
	ds_read_b128 a[24:27], v84
	s_nop 0
	v_add_u32_e32 v85, v100, v138
	ds_read_b128 a[20:23], v85 offset:36864
	s_nop 0
	s_nop 0
	ds_read_b128 a[16:19], v85 offset:32768
	s_nop 0
	s_nop 0
	s_nop 0
	s_nop 0
	s_nop 0
	s_nop 0
	v_mfma_f32_32x32x16_bf16 v[0:15], a[4:7], a[12:15], 0
	s_nop 0
	s_waitcnt lgkmcnt(0)
	v_mfma_f32_32x32x16_bf16 v[48:63], a[16:19], a[24:27], v[48:63]
	v_mfma_f32_32x32x16_bf16 v[32:47], a[20:23], a[24:27], v[32:47]
	v_mfma_f32_32x32x16_bf16 v[16:31], a[16:19], a[28:31], v[16:31]
	v_bitop3_b32 v86, v64, v103, 4 bitop3:0x36
	v_lshlrev_b32_e32 v139, 4, v86
	v_add_u32_e32 v86, v101, v139
	ds_read_b128 a[12:15], v86 offset:4096
	s_nop 0
	s_nop 0
	ds_read_b128 a[8:11], v86
	s_nop 0
	v_add_u32_e32 v87, v100, v139
	ds_read_b128 a[4:7], v87 offset:36864
	s_nop 0
	s_nop 0
	ds_read_b128 a[0:3], v87 offset:32768
	s_nop 0
	s_nop 0
	s_nop 0
	v_mfma_f32_32x32x16_bf16 v[0:15], a[20:23], a[28:31], v[0:15]
	s_nop 0
	s_nop 0
	s_nop 0
	s_nop 0
	s_waitcnt lgkmcnt(0)
	v_mfma_f32_32x32x16_bf16 v[48:63], a[0:3], a[8:11], v[48:63]
	v_mfma_f32_32x32x16_bf16 v[32:47], a[4:7], a[8:11], v[32:47]
	v_mfma_f32_32x32x16_bf16 v[16:31], a[0:3], a[12:15], v[16:31]
	v_bitop3_b32 v88, v64, v103, 6 bitop3:0x36
	v_lshlrev_b32_e32 v142, 4, v88
	v_add_u32_e32 v88, v101, v142
	ds_read_b128 a[28:31], v88 offset:4096
	s_nop 0
	s_nop 0
	ds_read_b128 a[24:27], v88
	s_nop 0
	v_add_u32_e32 v89, v100, v142
	ds_read_b128 a[20:23], v89 offset:36864
	s_nop 0
	s_nop 0
	ds_read_b128 a[16:19], v89 offset:32768
	s_nop 0
	s_nop 0
	s_nop 0
	v_lshlrev_b32_e32 v64, 4, v64
	v_lshl_or_b32 v64, v80, 8, v64
	v_add3_u32 v64, 0, v81, v64
	v_mfma_f32_32x32x16_bf16 v[0:15], a[4:7], a[12:15], v[0:15]
	s_nop 0
	s_nop 0
	s_nop 0
	s_nop 0
	s_waitcnt lgkmcnt(0)
	v_mfma_f32_32x32x16_bf16 v[48:63], a[16:19], a[24:27], v[48:63]
	v_mfma_f32_32x32x16_bf16 v[32:47], a[20:23], a[24:27], v[32:47]
	s_waitcnt vmcnt(6)
	s_waitcnt lgkmcnt(0)
	s_barrier
	ds_read_b128 a[12:15], v82 offset:53248
	ds_read_b128 a[8:11], v82 offset:49152
	v_mfma_f32_32x32x16_bf16 v[16:31], a[16:19], a[28:31], v[16:31]
	v_lshl_add_u64 v[158:159], v[66:67], 0, s[30:31]
	s_nop 0
	v_lshl_add_u64 v[160:161], v[68:69], 0, s[30:31]
	s_nop 0
	s_nop 0
	s_nop 0
	v_lshl_add_u64 v[162:163], v[70:71], 0, s[30:31]
	s_nop 0
	v_mfma_f32_32x32x16_bf16 v[0:15], a[20:23], a[28:31], v[0:15]
	s_and_b32 m0, s32, 7
	s_lshl_b32 m0, m0, 12
	s_add_i32 m0, m0, 0x0
	s_nop 0
	global_load_lds_dwordx4 v[158:159], off
	s_nop 0
	v_lshl_add_u64 v[164:165], v[72:73], 0, s[30:31]
	s_nop 0
	s_nop 0
	s_nop 0
	v_lshl_add_u64 v[166:167], v[74:75], 0, s[30:31]
	s_nop 0
	s_nop 0
	s_nop 0
	v_lshl_add_u64 v[168:169], v[76:77], 0, s[30:31]
	s_nop 0
	s_add_i32 s30, 0, 0xc000
	v_add_u32_e32 v90, s30, v132
	v_add_u32_e32 v92, v90, v143
	v_add_u32_e32 v90, v90, v144
	ds_read_b128 a[4:7], v90
	ds_read_b128 a[0:3], v92
	s_nop 0
	s_nop 0
	s_nop 0
	s_nop 0
	s_nop 0
	s_nop 0
	s_nop 0
	s_nop 0
	v_add_u32_e32 v91, s30, v138
	v_add_u32_e32 v93, v91, v143
	ds_read_b128 a[16:19], v93
	v_add_u32_e32 v91, v91, v144
	ds_read_b128 a[20:23], v91
	ds_read_b128 a[24:27], v84 offset:49152
	ds_read_b128 a[28:31], v84 offset:53248
	s_waitcnt lgkmcnt(4)
	v_mfma_f32_32x32x16_bf16 v[48:63], a[0:3], a[8:11], v[48:63]
	s_nop 0
	s_nop 0
	s_nop 0
	s_nop 0
	v_mfma_f32_32x32x16_bf16 v[32:47], a[4:7], a[8:11], v[32:47]
	s_and_b32 m0, s32, 7
	s_lshl_b32 m0, m0, 12
	s_add_i32 m0, m0, 0x400
	s_nop 0
	global_load_lds_dwordx4 v[160:161], off
	v_mfma_f32_32x32x16_bf16 v[16:31], a[0:3], a[12:15], v[16:31]
	v_mfma_f32_32x32x16_bf16 v[0:15], a[4:7], a[12:15], v[0:15]
	s_and_b32 m0, s32, 7
	s_lshl_b32 m0, m0, 12
	s_add_i32 m0, m0, 0x800
	s_nop 0
	global_load_lds_dwordx4 v[162:163], off
	s_nop 0
	s_nop 0
	s_nop 0
	s_nop 0
	v_add_u32_e32 v94, s30, v139
	v_add_u32_e32 v95, v94, v143
	ds_read_b128 a[0:3], v95
	v_add_u32_e32 v94, v94, v144
	ds_read_b128 a[4:7], v94
	ds_read_b128 a[8:11], v86 offset:49152
	ds_read_b128 a[12:15], v86 offset:53248
	s_waitcnt lgkmcnt(5)
	v_mfma_f32_32x32x16_bf16 v[48:63], a[16:19], a[24:27], v[48:63]
	v_mfma_f32_32x32x16_bf16 v[32:47], a[20:23], a[24:27], v[32:47]
	s_and_b32 m0, s32, 7
	s_lshl_b32 m0, m0, 12
	s_add_i32 m0, m0, 0xc00
	s_nop 0
	global_load_lds_dwordx4 v[164:165], off
	s_waitcnt lgkmcnt(4)
	v_mfma_f32_32x32x16_bf16 v[16:31], a[16:19], a[28:31], v[16:31]
	s_nop 0
	s_nop 0
	s_nop 0
	v_mfma_f32_32x32x16_bf16 v[0:15], a[20:23], a[28:31], v[0:15]
	s_and_b32 m0, s32, 7
	s_lshl_b32 m0, m0, 11
	s_add_i32 m0, m0, 0x8000
	s_nop 0
	global_load_lds_dwordx4 v[166:167], off
	s_nop 0
	s_nop 0
	s_nop 0
	s_nop 0
	v_add_u32_e32 v96, s30, v142
	v_add_u32_e32 v97, v96, v143
	ds_read_b128 a[16:19], v97
	v_add_u32_e32 v96, v96, v144
	ds_read_b128 a[20:23], v96
	ds_read_b128 a[24:27], v88 offset:49152
	ds_read_b128 a[28:31], v88 offset:53248
	s_waitcnt lgkmcnt(5)
	v_mfma_f32_32x32x16_bf16 v[48:63], a[0:3], a[8:11], v[48:63]
	v_mfma_f32_32x32x16_bf16 v[32:47], a[4:7], a[8:11], v[32:47]
	s_and_b32 m0, s32, 7
	s_lshl_b32 m0, m0, 11
	s_add_i32 m0, m0, 0x8400
	s_nop 0
	global_load_lds_dwordx4 v[168:169], off
	s_waitcnt lgkmcnt(4)
	v_mfma_f32_32x32x16_bf16 v[16:31], a[0:3], a[12:15], v[16:31]
	s_nop 0
	s_nop 0
	s_nop 0
	s_mov_b64 s[30:31], 0x200
	v_mfma_f32_32x32x16_bf16 v[0:15], a[4:7], a[12:15], v[0:15]
	s_nop 0
	s_nop 0
	s_nop 0
	s_nop 0
	s_waitcnt lgkmcnt(1)
	v_mfma_f32_32x32x16_bf16 v[48:63], a[16:19], a[24:27], v[48:63]
	v_mfma_f32_32x32x16_bf16 v[32:47], a[20:23], a[24:27], v[32:47]
	s_waitcnt vmcnt(6)
	s_waitcnt lgkmcnt(0)
	s_barrier
	v_add_u32_e32 v100, v145, v132
	ds_read_b128 a[8:11], v100
	v_add_u32_e32 v101, s3, v132
	v_add_u32_e32 v99, v101, v144
	ds_read_b128 a[4:7], v99
	s_nop 0
	v_add_u32_e32 v98, v101, v143
	v_or_b32_e32 v132, 0x1000, v134
	v_add_u32_e32 v101, v101, v132
	ds_read_b128 a[12:15], v101
	ds_read_b128 a[0:3], v98
	v_mfma_f32_32x32x16_bf16 v[16:31], a[16:19], a[28:31], v[16:31]
	v_lshl_add_u64 v[170:171], v[66:67], 0, s[30:31]
	s_nop 0
	v_lshl_add_u64 v[172:173], v[68:69], 0, s[30:31]
	s_nop 0
	s_nop 0
	s_nop 0
	v_lshl_add_u64 v[174:175], v[70:71], 0, s[30:31]
	s_nop 0
	v_mfma_f32_32x32x16_bf16 v[0:15], a[20:23], a[28:31], v[0:15]
	s_and_b32 m0, s32, 7
	s_lshl_b32 m0, m0, 12
	s_add_i32 m0, m0, 0xc000
	s_nop 0
	global_load_lds_dwordx4 v[170:171], off
	s_nop 0
	v_lshl_add_u64 v[176:177], v[72:73], 0, s[30:31]
	s_nop 0
	s_nop 0
	s_nop 0
	v_lshl_add_u64 v[178:179], v[74:75], 0, s[30:31]
	s_nop 0
	s_nop 0
	s_nop 0
	v_lshl_add_u64 v[180:181], v[76:77], 0, s[30:31]
	s_nop 0
	s_mov_b64 s[30:31], 0x280
	s_nop 0
	s_nop 0
	s_nop 0
	s_nop 0
	s_nop 0
	s_nop 0
	s_nop 0
	s_nop 0
	v_add_u32_e32 v105, s3, v138
	v_add_u32_e32 v102, v105, v143
	ds_read_b128 a[16:19], v102
	v_add_u32_e32 v103, v105, v144
	ds_read_b128 a[20:23], v103
	v_add_u32_e32 v104, v145, v138
	ds_read_b128 a[24:27], v104
	v_add_u32_e32 v105, v105, v132
	ds_read_b128 a[28:31], v105
	s_waitcnt lgkmcnt(4)
	v_mfma_f32_32x32x16_bf16 v[48:63], a[0:3], a[8:11], v[48:63]
	s_nop 0
	v_mfma_f32_32x32x16_bf16 v[32:47], a[4:7], a[8:11], v[32:47]
	s_and_b32 m0, s32, 7
	s_lshl_b32 m0, m0, 12
	s_add_i32 m0, m0, 0xc400
	s_nop 0
	global_load_lds_dwordx4 v[172:173], off
	s_nop 0
	s_nop 0
	s_nop 0
	s_nop 0
	s_nop 0
	v_mfma_f32_32x32x16_bf16 v[16:31], a[0:3], a[12:15], v[16:31]
	s_nop 0
	v_mfma_f32_32x32x16_bf16 v[0:15], a[4:7], a[12:15], v[0:15]
	s_and_b32 m0, s32, 7
	s_lshl_b32 m0, m0, 12
	s_add_i32 m0, m0, 0xc800
	s_nop 0
	global_load_lds_dwordx4 v[174:175], off
	s_nop 0
	s_nop 0
	s_nop 0
	v_add_u32_e32 v109, s3, v139
	v_add_u32_e32 v106, v109, v143
	ds_read_b128 a[0:3], v106
	v_add_u32_e32 v107, v109, v144
	ds_read_b128 a[4:7], v107
	v_add_u32_e32 v108, v145, v139
	ds_read_b128 a[8:11], v108
	v_add_u32_e32 v109, v109, v132
	ds_read_b128 a[12:15], v109
	s_waitcnt lgkmcnt(5)
	v_mfma_f32_32x32x16_bf16 v[48:63], a[16:19], a[24:27], v[48:63]
	v_mfma_f32_32x32x16_bf16 v[32:47], a[20:23], a[24:27], v[32:47]
	s_and_b32 m0, s32, 7
	s_lshl_b32 m0, m0, 12
	s_add_i32 m0, m0, 0xcc00
	s_nop 0
	global_load_lds_dwordx4 v[176:177], off
	s_waitcnt lgkmcnt(4)
	v_mfma_f32_32x32x16_bf16 v[16:31], a[16:19], a[28:31], v[16:31]
	s_nop 0
	s_nop 0
	s_nop 0
	s_nop 0
	s_nop 0
	s_nop 0
	v_mfma_f32_32x32x16_bf16 v[0:15], a[20:23], a[28:31], v[0:15]
	s_and_b32 m0, s32, 7
	s_lshl_b32 m0, m0, 11
	s_add_i32 m0, m0, 0x14000
	s_nop 0
	global_load_lds_dwordx4 v[178:179], off
	s_nop 0
	s_nop 0
	s_nop 0
	v_add_u32_e32 v113, s3, v142
	v_add_u32_e32 v110, v113, v143
	ds_read_b128 a[16:19], v110
	v_add_u32_e32 v111, v113, v144
	ds_read_b128 a[20:23], v111
	v_add_u32_e32 v112, v145, v142
	ds_read_b128 a[24:27], v112
	v_add_u32_e32 v113, v113, v132
	ds_read_b128 a[28:31], v113
	s_waitcnt lgkmcnt(5)
	v_mfma_f32_32x32x16_bf16 v[48:63], a[0:3], a[8:11], v[48:63]
	v_mfma_f32_32x32x16_bf16 v[32:47], a[4:7], a[8:11], v[32:47]
	s_and_b32 m0, s32, 7
	s_lshl_b32 m0, m0, 11
	s_add_i32 m0, m0, 0x14400
	s_nop 0
	global_load_lds_dwordx4 v[180:181], off
	s_waitcnt lgkmcnt(4)
	v_mfma_f32_32x32x16_bf16 v[16:31], a[0:3], a[12:15], v[16:31]
	s_nop 0
	s_nop 0
	s_nop 0
	s_nop 0
	s_nop 0
	s_nop 0
	v_mfma_f32_32x32x16_bf16 v[0:15], a[4:7], a[12:15], v[0:15]
	s_nop 0
	s_nop 0
	s_nop 0
	s_waitcnt lgkmcnt(1)
	v_mfma_f32_32x32x16_bf16 v[48:63], a[16:19], a[24:27], v[48:63]
	v_mfma_f32_32x32x16_bf16 v[32:47], a[20:23], a[24:27], v[32:47]
	s_waitcnt vmcnt(6)
	s_waitcnt lgkmcnt(0)
	s_barrier
	ds_read_b128 a[12:15], v82 offset:4096
	ds_read_b128 a[8:11], v82
	ds_read_b128 a[4:7], v83 offset:36864
	ds_read_b128 a[0:3], v83 offset:32768
	v_mfma_f32_32x32x16_bf16 v[16:31], a[16:19], a[28:31], v[16:31]
	v_lshl_add_u64 v[158:159], v[66:67], 0, s[30:31]
	s_nop 0
	v_lshl_add_u64 v[160:161], v[68:69], 0, s[30:31]
	s_nop 0
	s_nop 0
	s_nop 0
	v_lshl_add_u64 v[162:163], v[70:71], 0, s[30:31]
	s_nop 0
	v_mfma_f32_32x32x16_bf16 v[0:15], a[20:23], a[28:31], v[0:15]
	s_and_b32 m0, s32, 7
	s_lshl_b32 m0, m0, 12
	s_add_i32 m0, m0, 0x18000
	s_nop 0
	global_load_lds_dwordx4 v[158:159], off
	s_nop 0
	v_lshl_add_u64 v[164:165], v[72:73], 0, s[30:31]
	s_nop 0
	s_nop 0
	s_nop 0
	v_lshl_add_u64 v[166:167], v[74:75], 0, s[30:31]
	s_nop 0
	s_nop 0
	s_nop 0
	v_lshl_add_u64 v[168:169], v[76:77], 0, s[30:31]
	s_nop 0
	s_mov_b64 s[30:31], 0x300
	s_nop 0
	s_nop 0
	s_nop 0
	s_nop 0
	s_nop 0
	ds_read_b128 a[16:19], v85 offset:32768
	ds_read_b128 a[20:23], v85 offset:36864
	ds_read_b128 a[24:27], v84
	ds_read_b128 a[28:31], v84 offset:4096
	s_waitcnt lgkmcnt(4)
	v_mfma_f32_32x32x16_bf16 v[48:63], a[0:3], a[8:11], v[48:63]
	s_nop 0
	v_readfirstlane_b32 s38, v114
	v_mfma_f32_32x32x16_bf16 v[32:47], a[4:7], a[8:11], v[32:47]
	s_and_b32 m0, s32, 7
	s_lshl_b32 m0, m0, 12
	s_add_i32 m0, m0, 0x18400
	s_nop 0
	global_load_lds_dwordx4 v[160:161], off
	v_mfma_f32_32x32x16_bf16 v[16:31], a[0:3], a[12:15], v[16:31]
	v_mfma_f32_32x32x16_bf16 v[0:15], a[4:7], a[12:15], v[0:15]
	s_and_b32 m0, s32, 7
	s_lshl_b32 m0, m0, 12
	s_add_i32 m0, m0, 0x18800
	s_nop 0
	global_load_lds_dwordx4 v[162:163], off
	s_nop 0
	s_nop 0
	s_nop 0
	s_nop 0
	ds_read_b128 a[0:3], v87 offset:32768
	ds_read_b128 a[4:7], v87 offset:36864
	ds_read_b128 a[8:11], v86
	ds_read_b128 a[12:15], v86 offset:4096
	s_waitcnt lgkmcnt(5)
	v_mfma_f32_32x32x16_bf16 v[48:63], a[16:19], a[24:27], v[48:63]
	v_mfma_f32_32x32x16_bf16 v[32:47], a[20:23], a[24:27], v[32:47]
	s_and_b32 m0, s32, 7
	s_lshl_b32 m0, m0, 12
	s_add_i32 m0, m0, 0x18c00
	s_nop 0
	global_load_lds_dwordx4 v[164:165], off
	s_waitcnt lgkmcnt(4)
	v_mfma_f32_32x32x16_bf16 v[16:31], a[16:19], a[28:31], v[16:31]
	v_mfma_f32_32x32x16_bf16 v[0:15], a[20:23], a[28:31], v[0:15]
	s_and_b32 m0, s32, 7
	s_lshl_b32 m0, m0, 11
	s_add_i32 m0, m0, 0x20000
	s_nop 0
	global_load_lds_dwordx4 v[166:167], off
	s_nop 0
	s_nop 0
	s_nop 0
	s_nop 0
	ds_read_b128 a[16:19], v89 offset:32768
	ds_read_b128 a[20:23], v89 offset:36864
	ds_read_b128 a[24:27], v88
	ds_read_b128 a[28:31], v88 offset:4096
	s_waitcnt lgkmcnt(5)
	v_mfma_f32_32x32x16_bf16 v[48:63], a[0:3], a[8:11], v[48:63]
	v_mfma_f32_32x32x16_bf16 v[32:47], a[4:7], a[8:11], v[32:47]
	s_and_b32 m0, s32, 7
	s_lshl_b32 m0, m0, 11
	s_add_i32 m0, m0, 0x20400
	s_nop 0
	global_load_lds_dwordx4 v[168:169], off
	s_waitcnt lgkmcnt(4)
	v_mfma_f32_32x32x16_bf16 v[16:31], a[0:3], a[12:15], v[16:31]
	v_mfma_f32_32x32x16_bf16 v[0:15], a[4:7], a[12:15], v[0:15]
	s_nop 0
	s_nop 0
	s_nop 0
	s_nop 0
	s_waitcnt lgkmcnt(1)
	v_mfma_f32_32x32x16_bf16 v[48:63], a[16:19], a[24:27], v[48:63]
	v_mfma_f32_32x32x16_bf16 v[32:47], a[20:23], a[24:27], v[32:47]
	s_waitcnt vmcnt(6)
	s_waitcnt lgkmcnt(0)
	s_barrier
	ds_read_b128 a[12:15], v82 offset:53248
	ds_read_b128 a[8:11], v82 offset:49152
	ds_read_b128 a[4:7], v90
	ds_read_b128 a[0:3], v92
	v_mfma_f32_32x32x16_bf16 v[16:31], a[16:19], a[28:31], v[16:31]
	v_lshl_add_u64 v[170:171], v[66:67], 0, s[30:31]
	s_nop 0
	v_lshl_add_u64 v[172:173], v[68:69], 0, s[30:31]
	s_nop 0
	v_readfirstlane_b32 s39, v115
	s_nop 0
	v_lshl_add_u64 v[174:175], v[70:71], 0, s[30:31]
	s_nop 0
	v_mfma_f32_32x32x16_bf16 v[0:15], a[20:23], a[28:31], v[0:15]
	s_and_b32 m0, s32, 7
	s_lshl_b32 m0, m0, 12
	s_add_i32 m0, m0, 0x0
	s_nop 0
	global_load_lds_dwordx4 v[170:171], off
	s_nop 0
	v_lshl_add_u64 v[176:177], v[72:73], 0, s[30:31]
	s_nop 0
	v_readfirstlane_b32 s48, v116
	s_nop 0
	v_lshl_add_u64 v[178:179], v[74:75], 0, s[30:31]
	s_nop 0
	v_readfirstlane_b32 s49, v117
	s_nop 0
	v_lshl_add_u64 v[180:181], v[76:77], 0, s[30:31]
	s_nop 0
	s_mov_b64 s[30:31], 0x380
	s_nop 0
	s_nop 0
	s_nop 0
	s_nop 0
	s_nop 0
	ds_read_b128 a[16:19], v93
	ds_read_b128 a[20:23], v91
	ds_read_b128 a[24:27], v84 offset:49152
	ds_read_b128 a[28:31], v84 offset:53248
	s_waitcnt lgkmcnt(4)
	v_mfma_f32_32x32x16_bf16 v[48:63], a[0:3], a[8:11], v[48:63]
	s_nop 0
	v_readfirstlane_b32 s53, v118
	v_readfirstlane_b32 s54, v119
	v_mfma_f32_32x32x16_bf16 v[32:47], a[4:7], a[8:11], v[32:47]
	s_and_b32 m0, s32, 7
	s_lshl_b32 m0, m0, 12
	s_add_i32 m0, m0, 0x400
	s_nop 0
	global_load_lds_dwordx4 v[172:173], off
	v_mfma_f32_32x32x16_bf16 v[16:31], a[0:3], a[12:15], v[16:31]
	v_mfma_f32_32x32x16_bf16 v[0:15], a[4:7], a[12:15], v[0:15]
	s_and_b32 m0, s32, 7
	s_lshl_b32 m0, m0, 12
	s_add_i32 m0, m0, 0x800
	s_nop 0
	global_load_lds_dwordx4 v[174:175], off
	s_nop 0
	s_nop 0
	s_nop 0
	s_nop 0
	ds_read_b128 a[0:3], v95
	ds_read_b128 a[4:7], v94
	ds_read_b128 a[8:11], v86 offset:49152
	ds_read_b128 a[12:15], v86 offset:53248
	s_waitcnt lgkmcnt(5)
	v_mfma_f32_32x32x16_bf16 v[48:63], a[16:19], a[24:27], v[48:63]
	v_mfma_f32_32x32x16_bf16 v[32:47], a[20:23], a[24:27], v[32:47]
	s_and_b32 m0, s32, 7
	s_lshl_b32 m0, m0, 12
	s_add_i32 m0, m0, 0xc00
	s_nop 0
	global_load_lds_dwordx4 v[176:177], off
	s_waitcnt lgkmcnt(4)
	v_mfma_f32_32x32x16_bf16 v[16:31], a[16:19], a[28:31], v[16:31]
	v_mfma_f32_32x32x16_bf16 v[0:15], a[20:23], a[28:31], v[0:15]
	s_and_b32 m0, s32, 7
	s_lshl_b32 m0, m0, 11
	s_add_i32 m0, m0, 0x8000
	s_nop 0
	global_load_lds_dwordx4 v[178:179], off
	s_nop 0
	s_nop 0
	s_nop 0
	s_nop 0
	ds_read_b128 a[16:19], v97
	ds_read_b128 a[20:23], v96
	ds_read_b128 a[24:27], v88 offset:49152
	ds_read_b128 a[28:31], v88 offset:53248
	s_waitcnt lgkmcnt(5)
	v_mfma_f32_32x32x16_bf16 v[48:63], a[0:3], a[8:11], v[48:63]
	v_mfma_f32_32x32x16_bf16 v[32:47], a[4:7], a[8:11], v[32:47]
	s_and_b32 m0, s32, 7
	s_lshl_b32 m0, m0, 11
	s_add_i32 m0, m0, 0x8400
	s_nop 0
	global_load_lds_dwordx4 v[180:181], off
	s_waitcnt lgkmcnt(4)
	v_mfma_f32_32x32x16_bf16 v[16:31], a[0:3], a[12:15], v[16:31]
	v_mfma_f32_32x32x16_bf16 v[0:15], a[4:7], a[12:15], v[0:15]
	s_nop 0
	s_nop 0
	s_nop 0
	s_nop 0
	s_waitcnt lgkmcnt(1)
	v_mfma_f32_32x32x16_bf16 v[48:63], a[16:19], a[24:27], v[48:63]
	v_mfma_f32_32x32x16_bf16 v[32:47], a[20:23], a[24:27], v[32:47]
	s_waitcnt vmcnt(6)
	s_waitcnt lgkmcnt(0)
	s_barrier
	ds_read_b128 a[12:15], v101
	ds_read_b128 a[8:11], v100
	ds_read_b128 a[4:7], v99
	ds_read_b128 a[0:3], v98
	v_mfma_f32_32x32x16_bf16 v[16:31], a[16:19], a[28:31], v[16:31]
	v_lshl_add_u64 v[158:159], v[66:67], 0, s[30:31]
	s_nop 0
	v_lshl_add_u64 v[160:161], v[68:69], 0, s[30:31]
	s_nop 0
	v_readfirstlane_b32 s33, v121
	s_nop 0
	v_lshl_add_u64 v[162:163], v[70:71], 0, s[30:31]
	s_nop 0
	v_mfma_f32_32x32x16_bf16 v[0:15], a[20:23], a[28:31], v[0:15]
	s_and_b32 m0, s32, 7
	s_lshl_b32 m0, m0, 12
	s_add_i32 m0, m0, 0xc000
	s_nop 0
	global_load_lds_dwordx4 v[158:159], off
	s_nop 0
	v_lshl_add_u64 v[164:165], v[72:73], 0, s[30:31]
	s_nop 0
	v_readfirstlane_b32 s34, v122
	s_nop 0
	v_lshl_add_u64 v[166:167], v[74:75], 0, s[30:31]
	s_nop 0
	v_readfirstlane_b32 s35, v123
	s_nop 0
	v_lshl_add_u64 v[168:169], v[76:77], 0, s[30:31]
	s_nop 0
	s_mov_b64 s[30:31], 0x400
	s_nop 0
	s_nop 0
	s_nop 0
	s_nop 0
	s_nop 0
	ds_read_b128 a[16:19], v102
	ds_read_b128 a[20:23], v103
	ds_read_b128 a[24:27], v104
	ds_read_b128 a[28:31], v105
	s_waitcnt lgkmcnt(4)
	v_mfma_f32_32x32x16_bf16 v[48:63], a[0:3], a[8:11], v[48:63]
	s_nop 0
	v_readfirstlane_b32 s1, v126
	v_readfirstlane_b32 s36, v124
	v_readfirstlane_b32 s37, v125
	v_mfma_f32_32x32x16_bf16 v[32:47], a[4:7], a[8:11], v[32:47]
	s_and_b32 m0, s32, 7
	s_lshl_b32 m0, m0, 12
	s_add_i32 m0, m0, 0xc400
	s_nop 0
	global_load_lds_dwordx4 v[160:161], off
	v_mfma_f32_32x32x16_bf16 v[16:31], a[0:3], a[12:15], v[16:31]
	v_mfma_f32_32x32x16_bf16 v[0:15], a[4:7], a[12:15], v[0:15]
	s_and_b32 m0, s32, 7
	s_lshl_b32 m0, m0, 12
	s_add_i32 m0, m0, 0xc800
	s_nop 0
	global_load_lds_dwordx4 v[162:163], off
	s_nop 0
	s_nop 0
	s_nop 0
	s_nop 0
	ds_read_b128 a[0:3], v106
	ds_read_b128 a[4:7], v107
	ds_read_b128 a[8:11], v108
	ds_read_b128 a[12:15], v109
	s_waitcnt lgkmcnt(5)
	v_mfma_f32_32x32x16_bf16 v[48:63], a[16:19], a[24:27], v[48:63]
	v_mfma_f32_32x32x16_bf16 v[32:47], a[20:23], a[24:27], v[32:47]
	s_and_b32 m0, s32, 7
	s_lshl_b32 m0, m0, 12
	s_add_i32 m0, m0, 0xcc00
	s_nop 0
	global_load_lds_dwordx4 v[164:165], off
	s_waitcnt lgkmcnt(4)
	v_mfma_f32_32x32x16_bf16 v[16:31], a[16:19], a[28:31], v[16:31]
	v_mfma_f32_32x32x16_bf16 v[0:15], a[20:23], a[28:31], v[0:15]
	s_and_b32 m0, s32, 7
	s_lshl_b32 m0, m0, 11
	s_add_i32 m0, m0, 0x14000
	s_nop 0
	global_load_lds_dwordx4 v[166:167], off
	s_nop 0
	s_nop 0
	s_nop 0
	s_nop 0
	ds_read_b128 a[16:19], v110
	ds_read_b128 a[20:23], v111
	ds_read_b128 a[24:27], v112
	ds_read_b128 a[28:31], v113
	s_waitcnt lgkmcnt(5)
	v_mfma_f32_32x32x16_bf16 v[48:63], a[0:3], a[8:11], v[48:63]
	v_mfma_f32_32x32x16_bf16 v[32:47], a[4:7], a[8:11], v[32:47]
	s_and_b32 m0, s32, 7
	s_lshl_b32 m0, m0, 11
	s_add_i32 m0, m0, 0x14400
	s_nop 0
	global_load_lds_dwordx4 v[168:169], off
	s_waitcnt lgkmcnt(4)
	v_mfma_f32_32x32x16_bf16 v[16:31], a[0:3], a[12:15], v[16:31]
	v_mfma_f32_32x32x16_bf16 v[0:15], a[4:7], a[12:15], v[0:15]
	s_nop 0
	s_nop 0
	s_nop 0
	s_nop 0
	s_waitcnt lgkmcnt(1)
	v_mfma_f32_32x32x16_bf16 v[48:63], a[16:19], a[24:27], v[48:63]
	v_mfma_f32_32x32x16_bf16 v[32:47], a[20:23], a[24:27], v[32:47]
	s_waitcnt vmcnt(6)
	s_waitcnt lgkmcnt(0)
	s_barrier
	ds_read_b128 a[12:15], v82 offset:4096
	ds_read_b128 a[8:11], v82
	ds_read_b128 a[4:7], v83 offset:36864
	ds_read_b128 a[0:3], v83 offset:32768
	v_mfma_f32_32x32x16_bf16 v[16:31], a[16:19], a[28:31], v[16:31]
	v_lshl_add_u64 v[170:171], v[66:67], 0, s[30:31]
	s_nop 0
	v_lshl_add_u64 v[172:173], v[68:69], 0, s[30:31]
	s_nop 0
	v_readfirstlane_b32 s20, v127
	s_nop 0
	v_lshl_add_u64 v[174:175], v[70:71], 0, s[30:31]
	s_nop 0
	v_mfma_f32_32x32x16_bf16 v[0:15], a[20:23], a[28:31], v[0:15]
	s_and_b32 m0, s32, 7
	s_lshl_b32 m0, m0, 12
	s_add_i32 m0, m0, 0x18000
	s_nop 0
	global_load_lds_dwordx4 v[170:171], off
	s_nop 0
	v_lshl_add_u64 v[176:177], v[72:73], 0, s[30:31]
	s_nop 0
	v_readfirstlane_b32 s21, v128
	s_nop 0
	v_lshl_add_u64 v[178:179], v[74:75], 0, s[30:31]
	s_nop 0
	v_readfirstlane_b32 s23, v129
	s_nop 0
	v_lshl_add_u64 v[180:181], v[76:77], 0, s[30:31]
	s_nop 0
	s_mov_b64 s[28:29], 0x480
	s_nop 0
	s_nop 0
	s_nop 0
	s_nop 0
	s_nop 0
	ds_read_b128 a[16:19], v85 offset:32768
	ds_read_b128 a[20:23], v85 offset:36864
	ds_read_b128 a[24:27], v84
	ds_read_b128 a[28:31], v84 offset:4096
	s_waitcnt lgkmcnt(4)
	v_mfma_f32_32x32x16_bf16 v[48:63], a[0:3], a[8:11], v[48:63]
	s_nop 0
	v_lshl_add_u64 v[162:163], v[70:71], 0, s[28:29]
	v_readfirstlane_b32 s24, v131
	s_mov_b64 s[30:31], 0x500
	v_mfma_f32_32x32x16_bf16 v[32:47], a[4:7], a[8:11], v[32:47]
	s_and_b32 m0, s32, 7
	s_lshl_b32 m0, m0, 12
	s_add_i32 m0, m0, 0x18400
	s_nop 0
	global_load_lds_dwordx4 v[172:173], off
	v_mfma_f32_32x32x16_bf16 v[16:31], a[0:3], a[12:15], v[16:31]
	v_mfma_f32_32x32x16_bf16 v[0:15], a[4:7], a[12:15], v[0:15]
	s_and_b32 m0, s32, 7
	s_lshl_b32 m0, m0, 12
	s_add_i32 m0, m0, 0x18800
	s_nop 0
	global_load_lds_dwordx4 v[174:175], off
	s_nop 0
	s_nop 0
	s_nop 0
	s_nop 0
	ds_read_b128 a[0:3], v87 offset:32768
	ds_read_b128 a[4:7], v87 offset:36864
	ds_read_b128 a[8:11], v86
	ds_read_b128 a[12:15], v86 offset:4096
	s_waitcnt lgkmcnt(5)
	v_mfma_f32_32x32x16_bf16 v[48:63], a[16:19], a[24:27], v[48:63]
	v_mfma_f32_32x32x16_bf16 v[32:47], a[20:23], a[24:27], v[32:47]
	s_and_b32 m0, s32, 7
	s_lshl_b32 m0, m0, 12
	s_add_i32 m0, m0, 0x18c00
	s_nop 0
	global_load_lds_dwordx4 v[176:177], off
	s_waitcnt lgkmcnt(4)
	v_mfma_f32_32x32x16_bf16 v[16:31], a[16:19], a[28:31], v[16:31]
	v_mfma_f32_32x32x16_bf16 v[0:15], a[20:23], a[28:31], v[0:15]
	s_and_b32 m0, s32, 7
	s_lshl_b32 m0, m0, 11
	s_add_i32 m0, m0, 0x20000
	s_nop 0
	global_load_lds_dwordx4 v[178:179], off
	s_nop 0
	s_nop 0
	s_nop 0
	s_nop 0
	ds_read_b128 a[16:19], v89 offset:32768
	ds_read_b128 a[20:23], v89 offset:36864
	ds_read_b128 a[24:27], v88
	ds_read_b128 a[28:31], v88 offset:4096
	s_waitcnt lgkmcnt(5)
	v_mfma_f32_32x32x16_bf16 v[48:63], a[0:3], a[8:11], v[48:63]
	v_mfma_f32_32x32x16_bf16 v[32:47], a[4:7], a[8:11], v[32:47]
	s_and_b32 m0, s32, 7
	s_lshl_b32 m0, m0, 11
	s_add_i32 m0, m0, 0x20400
	s_nop 0
	global_load_lds_dwordx4 v[180:181], off
	s_waitcnt lgkmcnt(4)
	v_mfma_f32_32x32x16_bf16 v[16:31], a[0:3], a[12:15], v[16:31]
	v_mfma_f32_32x32x16_bf16 v[0:15], a[4:7], a[12:15], v[0:15]
	s_nop 0
	s_nop 0
	s_nop 0
	s_nop 0
	s_waitcnt lgkmcnt(1)
	v_mfma_f32_32x32x16_bf16 v[48:63], a[16:19], a[24:27], v[48:63]
	v_mfma_f32_32x32x16_bf16 v[32:47], a[20:23], a[24:27], v[32:47]
	s_waitcnt vmcnt(6)
	s_waitcnt lgkmcnt(0)
	s_barrier
	ds_read_b128 a[12:15], v82 offset:53248
	ds_read_b128 a[8:11], v82 offset:49152
	ds_read_b128 a[4:7], v90
	ds_read_b128 a[0:3], v92
	v_mfma_f32_32x32x16_bf16 v[16:31], a[16:19], a[28:31], v[16:31]
	v_lshl_add_u64 v[158:159], v[66:67], 0, s[28:29]
	s_nop 0
	v_lshl_add_u64 v[160:161], v[68:69], 0, s[28:29]
	s_nop 0
	s_nop 0
	s_nop 0
	s_nop 0
	v_mfma_f32_32x32x16_bf16 v[0:15], a[20:23], a[28:31], v[0:15]
	s_and_b32 m0, s32, 7
	s_lshl_b32 m0, m0, 12
	s_add_i32 m0, m0, 0x0
	s_nop 0
	global_load_lds_dwordx4 v[158:159], off
	s_nop 0
	v_lshl_add_u64 v[164:165], v[72:73], 0, s[28:29]
	s_nop 0
	s_nop 0
	s_nop 0
	v_lshl_add_u64 v[166:167], v[74:75], 0, s[28:29]
	s_nop 0
	s_nop 0
	s_nop 0
	v_lshl_add_u64 v[168:169], v[76:77], 0, s[28:29]
	v_readfirstlane_b32 s28, v130
	s_nop 0
	v_readfirstlane_b32 s29, v120
	s_nop 0
	s_nop 0
	s_nop 0
	s_nop 0
	s_nop 0
	ds_read_b128 a[16:19], v93
	ds_read_b128 a[20:23], v91
	ds_read_b128 a[24:27], v84 offset:49152
	ds_read_b128 a[28:31], v84 offset:53248
	s_waitcnt lgkmcnt(4)
	v_mfma_f32_32x32x16_bf16 v[48:63], a[0:3], a[8:11], v[48:63]
	s_nop 0
	v_lshl_add_u64 v[174:175], v[70:71], 0, s[30:31]
	v_mfma_f32_32x32x16_bf16 v[32:47], a[4:7], a[8:11], v[32:47]
	s_and_b32 m0, s32, 7
	s_lshl_b32 m0, m0, 12
	s_add_i32 m0, m0, 0x400
	s_nop 0
	global_load_lds_dwordx4 v[160:161], off
	v_mfma_f32_32x32x16_bf16 v[16:31], a[0:3], a[12:15], v[16:31]
	v_mfma_f32_32x32x16_bf16 v[0:15], a[4:7], a[12:15], v[0:15]
	s_and_b32 m0, s32, 7
	s_lshl_b32 m0, m0, 12
	s_add_i32 m0, m0, 0x800
	s_nop 0
	global_load_lds_dwordx4 v[162:163], off
	s_nop 0
	s_nop 0
	s_nop 0
	s_nop 0
	ds_read_b128 a[0:3], v95
	ds_read_b128 a[4:7], v94
	ds_read_b128 a[8:11], v86 offset:49152
	ds_read_b128 a[12:15], v86 offset:53248
	s_waitcnt lgkmcnt(5)
	v_mfma_f32_32x32x16_bf16 v[48:63], a[16:19], a[24:27], v[48:63]
	v_mfma_f32_32x32x16_bf16 v[32:47], a[20:23], a[24:27], v[32:47]
	s_and_b32 m0, s32, 7
	s_lshl_b32 m0, m0, 12
	s_add_i32 m0, m0, 0xc00
	s_nop 0
	global_load_lds_dwordx4 v[164:165], off
	s_waitcnt lgkmcnt(4)
	v_mfma_f32_32x32x16_bf16 v[16:31], a[16:19], a[28:31], v[16:31]
	v_mfma_f32_32x32x16_bf16 v[0:15], a[20:23], a[28:31], v[0:15]
	s_and_b32 m0, s32, 7
	s_lshl_b32 m0, m0, 11
	s_add_i32 m0, m0, 0x8000
	s_nop 0
	global_load_lds_dwordx4 v[166:167], off
	s_nop 0
	s_nop 0
	s_nop 0
	s_nop 0
	ds_read_b128 a[16:19], v97
	ds_read_b128 a[20:23], v96
	ds_read_b128 a[24:27], v88 offset:49152
	ds_read_b128 a[28:31], v88 offset:53248
	s_waitcnt lgkmcnt(5)
	v_mfma_f32_32x32x16_bf16 v[48:63], a[0:3], a[8:11], v[48:63]
	v_mfma_f32_32x32x16_bf16 v[32:47], a[4:7], a[8:11], v[32:47]
	s_and_b32 m0, s32, 7
	s_lshl_b32 m0, m0, 11
	s_add_i32 m0, m0, 0x8400
	s_nop 0
	global_load_lds_dwordx4 v[168:169], off
	s_waitcnt lgkmcnt(4)
	v_mfma_f32_32x32x16_bf16 v[16:31], a[0:3], a[12:15], v[16:31]
	v_mfma_f32_32x32x16_bf16 v[0:15], a[4:7], a[12:15], v[0:15]
	s_nop 0
	s_nop 0
	s_nop 0
	s_nop 0
	s_waitcnt lgkmcnt(1)
	v_mfma_f32_32x32x16_bf16 v[48:63], a[16:19], a[24:27], v[48:63]
	v_mfma_f32_32x32x16_bf16 v[32:47], a[20:23], a[24:27], v[32:47]
	s_waitcnt vmcnt(6)
	s_waitcnt lgkmcnt(0)
	s_barrier
	ds_read_b128 a[12:15], v101
	ds_read_b128 a[8:11], v100
	ds_read_b128 a[4:7], v99
	ds_read_b128 a[0:3], v98
	v_mfma_f32_32x32x16_bf16 v[16:31], a[16:19], a[28:31], v[16:31]
	v_lshl_add_u64 v[170:171], v[66:67], 0, s[30:31]
	s_nop 0
	v_lshl_add_u64 v[172:173], v[68:69], 0, s[30:31]
	s_nop 0
	s_nop 0
	s_nop 0
	s_nop 0
	v_mfma_f32_32x32x16_bf16 v[0:15], a[20:23], a[28:31], v[0:15]
	s_and_b32 m0, s32, 7
	s_lshl_b32 m0, m0, 12
	s_add_i32 m0, m0, 0xc000
	s_nop 0
	global_load_lds_dwordx4 v[170:171], off
	s_nop 0
	v_lshl_add_u64 v[176:177], v[72:73], 0, s[30:31]
	s_nop 0
	s_nop 0
	s_nop 0
	v_lshl_add_u64 v[178:179], v[74:75], 0, s[30:31]
	s_nop 0
	s_nop 0
	s_nop 0
	v_lshl_add_u64 v[180:181], v[76:77], 0, s[30:31]
	s_nop 0
	s_mov_b64 s[30:31], 0x580
	s_nop 0
	s_nop 0
	s_nop 0
	s_nop 0
	s_nop 0
	ds_read_b128 a[16:19], v102
	ds_read_b128 a[20:23], v103
	ds_read_b128 a[24:27], v104
	ds_read_b128 a[28:31], v105
	s_waitcnt lgkmcnt(4)
	v_mfma_f32_32x32x16_bf16 v[48:63], a[0:3], a[8:11], v[48:63]
	s_nop 0
	v_lshl_add_u64 v[162:163], v[70:71], 0, s[30:31]
	v_mfma_f32_32x32x16_bf16 v[32:47], a[4:7], a[8:11], v[32:47]
	s_and_b32 m0, s32, 7
	s_lshl_b32 m0, m0, 12
	s_add_i32 m0, m0, 0xc400
	s_nop 0
	global_load_lds_dwordx4 v[172:173], off
	v_mfma_f32_32x32x16_bf16 v[16:31], a[0:3], a[12:15], v[16:31]
	v_mfma_f32_32x32x16_bf16 v[0:15], a[4:7], a[12:15], v[0:15]
	s_and_b32 m0, s32, 7
	s_lshl_b32 m0, m0, 12
	s_add_i32 m0, m0, 0xc800
	s_nop 0
	global_load_lds_dwordx4 v[174:175], off
	s_nop 0
	s_nop 0
	s_nop 0
	s_nop 0
	ds_read_b128 a[0:3], v106
	ds_read_b128 a[4:7], v107
	ds_read_b128 a[8:11], v108
	ds_read_b128 a[12:15], v109
	s_waitcnt lgkmcnt(5)
	v_mfma_f32_32x32x16_bf16 v[48:63], a[16:19], a[24:27], v[48:63]
	v_mfma_f32_32x32x16_bf16 v[32:47], a[20:23], a[24:27], v[32:47]
	s_and_b32 m0, s32, 7
	s_lshl_b32 m0, m0, 12
	s_add_i32 m0, m0, 0xcc00
	s_nop 0
	global_load_lds_dwordx4 v[176:177], off
	s_waitcnt lgkmcnt(4)
	v_mfma_f32_32x32x16_bf16 v[16:31], a[16:19], a[28:31], v[16:31]
	v_mfma_f32_32x32x16_bf16 v[0:15], a[20:23], a[28:31], v[0:15]
	s_and_b32 m0, s32, 7
	s_lshl_b32 m0, m0, 11
	s_add_i32 m0, m0, 0x14000
	s_nop 0
	global_load_lds_dwordx4 v[178:179], off
	s_nop 0
	s_nop 0
	s_nop 0
	s_nop 0
	ds_read_b128 a[16:19], v110
	ds_read_b128 a[20:23], v111
	ds_read_b128 a[24:27], v112
	ds_read_b128 a[28:31], v113
	s_waitcnt lgkmcnt(5)
	v_mfma_f32_32x32x16_bf16 v[48:63], a[0:3], a[8:11], v[48:63]
	v_mfma_f32_32x32x16_bf16 v[32:47], a[4:7], a[8:11], v[32:47]
	s_and_b32 m0, s32, 7
	s_lshl_b32 m0, m0, 11
	s_add_i32 m0, m0, 0x14400
	s_nop 0
	global_load_lds_dwordx4 v[180:181], off
	s_waitcnt lgkmcnt(4)
	v_mfma_f32_32x32x16_bf16 v[16:31], a[0:3], a[12:15], v[16:31]
	v_mfma_f32_32x32x16_bf16 v[0:15], a[4:7], a[12:15], v[0:15]
	s_nop 0
	s_nop 0
	s_nop 0
	s_nop 0
	s_waitcnt lgkmcnt(1)
	v_mfma_f32_32x32x16_bf16 v[48:63], a[16:19], a[24:27], v[48:63]
	v_mfma_f32_32x32x16_bf16 v[32:47], a[20:23], a[24:27], v[32:47]
	s_waitcnt vmcnt(6)
	s_waitcnt lgkmcnt(0)
	s_barrier
	ds_read_b128 a[12:15], v82 offset:4096
	ds_read_b128 a[8:11], v82
	ds_read_b128 a[4:7], v83 offset:36864
	ds_read_b128 a[0:3], v83 offset:32768
	v_mfma_f32_32x32x16_bf16 v[16:31], a[16:19], a[28:31], v[16:31]
	v_lshl_add_u64 v[158:159], v[66:67], 0, s[30:31]
	s_nop 0
	v_lshl_add_u64 v[160:161], v[68:69], 0, s[30:31]
	s_nop 0
	s_nop 0
	s_nop 0
	s_nop 0
	v_mfma_f32_32x32x16_bf16 v[0:15], a[20:23], a[28:31], v[0:15]
	s_and_b32 m0, s32, 7
	s_lshl_b32 m0, m0, 12
	s_add_i32 m0, m0, 0x18000
	s_nop 0
	global_load_lds_dwordx4 v[158:159], off
	s_nop 0
	v_lshl_add_u64 v[164:165], v[72:73], 0, s[30:31]
	s_nop 0
	s_nop 0
	s_nop 0
	v_lshl_add_u64 v[166:167], v[74:75], 0, s[30:31]
	s_nop 0
	s_nop 0
	s_nop 0
	v_lshl_add_u64 v[168:169], v[76:77], 0, s[30:31]
	s_nop 0
	s_mov_b64 s[30:31], 0x600
	s_nop 0
	s_nop 0
	s_nop 0
	s_nop 0
	s_nop 0
	ds_read_b128 a[16:19], v85 offset:32768
	ds_read_b128 a[20:23], v85 offset:36864
	ds_read_b128 a[24:27], v84
	ds_read_b128 a[28:31], v84 offset:4096
	s_waitcnt lgkmcnt(4)
	v_mfma_f32_32x32x16_bf16 v[48:63], a[0:3], a[8:11], v[48:63]
	s_nop 0
	v_mfma_f32_32x32x16_bf16 v[32:47], a[4:7], a[8:11], v[32:47]
	s_and_b32 m0, s32, 7
	s_lshl_b32 m0, m0, 12
	s_add_i32 m0, m0, 0x18400
	s_nop 0
	global_load_lds_dwordx4 v[160:161], off
	v_mfma_f32_32x32x16_bf16 v[16:31], a[0:3], a[12:15], v[16:31]
	v_mfma_f32_32x32x16_bf16 v[0:15], a[4:7], a[12:15], v[0:15]
	s_and_b32 m0, s32, 7
	s_lshl_b32 m0, m0, 12
	s_add_i32 m0, m0, 0x18800
	s_nop 0
	global_load_lds_dwordx4 v[162:163], off
	s_nop 0
	s_nop 0
	s_nop 0
	s_nop 0
	ds_read_b128 a[0:3], v87 offset:32768
	ds_read_b128 a[4:7], v87 offset:36864
	ds_read_b128 a[8:11], v86
	ds_read_b128 a[12:15], v86 offset:4096
	s_waitcnt lgkmcnt(5)
	v_mfma_f32_32x32x16_bf16 v[48:63], a[16:19], a[24:27], v[48:63]
	v_mfma_f32_32x32x16_bf16 v[32:47], a[20:23], a[24:27], v[32:47]
	s_and_b32 m0, s32, 7
	s_lshl_b32 m0, m0, 12
	s_add_i32 m0, m0, 0x18c00
	s_nop 0
	global_load_lds_dwordx4 v[164:165], off
	s_waitcnt lgkmcnt(4)
	v_mfma_f32_32x32x16_bf16 v[16:31], a[16:19], a[28:31], v[16:31]
	v_mfma_f32_32x32x16_bf16 v[0:15], a[20:23], a[28:31], v[0:15]
	s_and_b32 m0, s32, 7
	s_lshl_b32 m0, m0, 11
	s_add_i32 m0, m0, 0x20000
	s_nop 0
	global_load_lds_dwordx4 v[166:167], off
	s_nop 0
	s_nop 0
	s_nop 0
	s_nop 0
	ds_read_b128 a[16:19], v89 offset:32768
	ds_read_b128 a[20:23], v89 offset:36864
	ds_read_b128 a[24:27], v88
	ds_read_b128 a[28:31], v88 offset:4096
	s_waitcnt lgkmcnt(5)
	v_mfma_f32_32x32x16_bf16 v[48:63], a[0:3], a[8:11], v[48:63]
	v_mfma_f32_32x32x16_bf16 v[32:47], a[4:7], a[8:11], v[32:47]
	s_and_b32 m0, s32, 7
	s_lshl_b32 m0, m0, 11
	s_add_i32 m0, m0, 0x20400
	s_nop 0
	global_load_lds_dwordx4 v[168:169], off
	s_waitcnt lgkmcnt(4)
	v_mfma_f32_32x32x16_bf16 v[16:31], a[0:3], a[12:15], v[16:31]
	v_mfma_f32_32x32x16_bf16 v[0:15], a[4:7], a[12:15], v[0:15]
	s_nop 0
	s_nop 0
	s_nop 0
	s_nop 0
	s_waitcnt lgkmcnt(1)
	v_mfma_f32_32x32x16_bf16 v[48:63], a[16:19], a[24:27], v[48:63]
	v_mfma_f32_32x32x16_bf16 v[32:47], a[20:23], a[24:27], v[32:47]
	s_waitcnt vmcnt(6)
	s_waitcnt lgkmcnt(0)
	s_barrier
	ds_read_b128 a[12:15], v82 offset:53248
	ds_read_b128 a[8:11], v82 offset:49152
	ds_read_b128 a[4:7], v90
	ds_read_b128 a[0:3], v92
	v_mfma_f32_32x32x16_bf16 v[16:31], a[16:19], a[28:31], v[16:31]
	v_lshl_add_u64 v[170:171], v[66:67], 0, s[30:31]
	s_nop 0
	v_lshl_add_u64 v[172:173], v[68:69], 0, s[30:31]
	s_nop 0
	s_nop 0
	s_nop 0
	v_lshl_add_u64 v[174:175], v[70:71], 0, s[30:31]
	s_nop 0
	v_mfma_f32_32x32x16_bf16 v[0:15], a[20:23], a[28:31], v[0:15]
	s_and_b32 m0, s32, 7
	s_lshl_b32 m0, m0, 12
	s_add_i32 m0, m0, 0x0
	s_nop 0
	global_load_lds_dwordx4 v[170:171], off
	s_nop 0
	v_lshl_add_u64 v[176:177], v[72:73], 0, s[30:31]
	s_nop 0
	s_nop 0
	s_nop 0
	v_lshl_add_u64 v[178:179], v[74:75], 0, s[30:31]
	s_nop 0
	s_nop 0
	s_nop 0
	v_lshl_add_u64 v[180:181], v[76:77], 0, s[30:31]
	s_nop 0
	s_mov_b64 s[30:31], 0x680
	s_nop 0
	s_nop 0
	s_nop 0
	s_nop 0
	s_nop 0
	ds_read_b128 a[16:19], v93
	ds_read_b128 a[20:23], v91
	ds_read_b128 a[24:27], v84 offset:49152
	ds_read_b128 a[28:31], v84 offset:53248
	s_waitcnt lgkmcnt(4)
	v_mfma_f32_32x32x16_bf16 v[48:63], a[0:3], a[8:11], v[48:63]
	s_nop 0
	v_mfma_f32_32x32x16_bf16 v[32:47], a[4:7], a[8:11], v[32:47]
	s_and_b32 m0, s32, 7
	s_lshl_b32 m0, m0, 12
	s_add_i32 m0, m0, 0x400
	s_nop 0
	global_load_lds_dwordx4 v[172:173], off
	v_mfma_f32_32x32x16_bf16 v[16:31], a[0:3], a[12:15], v[16:31]
	v_mfma_f32_32x32x16_bf16 v[0:15], a[4:7], a[12:15], v[0:15]
	s_and_b32 m0, s32, 7
	s_lshl_b32 m0, m0, 12
	s_add_i32 m0, m0, 0x800
	s_nop 0
	global_load_lds_dwordx4 v[174:175], off
	s_nop 0
	s_nop 0
	s_nop 0
	s_nop 0
	ds_read_b128 a[0:3], v95
	ds_read_b128 a[4:7], v94
	ds_read_b128 a[8:11], v86 offset:49152
	ds_read_b128 a[12:15], v86 offset:53248
	s_waitcnt lgkmcnt(5)
	v_mfma_f32_32x32x16_bf16 v[48:63], a[16:19], a[24:27], v[48:63]
	v_mfma_f32_32x32x16_bf16 v[32:47], a[20:23], a[24:27], v[32:47]
	s_and_b32 m0, s32, 7
	s_lshl_b32 m0, m0, 12
	s_add_i32 m0, m0, 0xc00
	s_nop 0
	global_load_lds_dwordx4 v[176:177], off
	s_waitcnt lgkmcnt(4)
	v_mfma_f32_32x32x16_bf16 v[16:31], a[16:19], a[28:31], v[16:31]
	v_mfma_f32_32x32x16_bf16 v[0:15], a[20:23], a[28:31], v[0:15]
	s_and_b32 m0, s32, 7
	s_lshl_b32 m0, m0, 11
	s_add_i32 m0, m0, 0x8000
	s_nop 0
	global_load_lds_dwordx4 v[178:179], off
	s_nop 0
	s_nop 0
	s_nop 0
	s_nop 0
	ds_read_b128 a[16:19], v97
	ds_read_b128 a[20:23], v96
	ds_read_b128 a[24:27], v88 offset:49152
	ds_read_b128 a[28:31], v88 offset:53248
	s_waitcnt lgkmcnt(5)
	v_mfma_f32_32x32x16_bf16 v[48:63], a[0:3], a[8:11], v[48:63]
	v_mfma_f32_32x32x16_bf16 v[32:47], a[4:7], a[8:11], v[32:47]
	s_and_b32 m0, s32, 7
	s_lshl_b32 m0, m0, 11
	s_add_i32 m0, m0, 0x8400
	s_nop 0
	global_load_lds_dwordx4 v[180:181], off
	s_waitcnt lgkmcnt(4)
	v_mfma_f32_32x32x16_bf16 v[16:31], a[0:3], a[12:15], v[16:31]
	v_mfma_f32_32x32x16_bf16 v[0:15], a[4:7], a[12:15], v[0:15]
	s_nop 0
	s_nop 0
	s_nop 0
	s_nop 0
	s_waitcnt lgkmcnt(1)
	v_mfma_f32_32x32x16_bf16 v[48:63], a[16:19], a[24:27], v[48:63]
	v_mfma_f32_32x32x16_bf16 v[32:47], a[20:23], a[24:27], v[32:47]
	s_waitcnt vmcnt(6)
	s_waitcnt lgkmcnt(0)
	s_barrier
	ds_read_b128 a[12:15], v101
	ds_read_b128 a[8:11], v100
	ds_read_b128 a[4:7], v99
	ds_read_b128 a[0:3], v98
	v_mfma_f32_32x32x16_bf16 v[16:31], a[16:19], a[28:31], v[16:31]
	v_lshl_add_u64 v[158:159], v[66:67], 0, s[30:31]
	s_nop 0
	v_lshl_add_u64 v[160:161], v[68:69], 0, s[30:31]
	s_nop 0
	s_nop 0
	s_nop 0
	v_lshl_add_u64 v[162:163], v[70:71], 0, s[30:31]
	s_nop 0
	v_mfma_f32_32x32x16_bf16 v[0:15], a[20:23], a[28:31], v[0:15]
	s_and_b32 m0, s32, 7
	s_lshl_b32 m0, m0, 12
	s_add_i32 m0, m0, 0xc000
	s_nop 0
	global_load_lds_dwordx4 v[158:159], off
	s_nop 0
	v_lshl_add_u64 v[164:165], v[72:73], 0, s[30:31]
	s_nop 0
	s_nop 0
	s_nop 0
	v_lshl_add_u64 v[166:167], v[74:75], 0, s[30:31]
	s_nop 0
	s_nop 0
	s_nop 0
	v_lshl_add_u64 v[168:169], v[76:77], 0, s[30:31]
	s_nop 0
	s_mov_b64 s[30:31], 0x700
	s_nop 0
	s_nop 0
	s_nop 0
	s_nop 0
	s_nop 0
	ds_read_b128 a[16:19], v102
	ds_read_b128 a[20:23], v103
	ds_read_b128 a[24:27], v104
	ds_read_b128 a[28:31], v105
	s_waitcnt lgkmcnt(4)
	v_mfma_f32_32x32x16_bf16 v[48:63], a[0:3], a[8:11], v[48:63]
	s_nop 0
	v_mfma_f32_32x32x16_bf16 v[32:47], a[4:7], a[8:11], v[32:47]
	s_and_b32 m0, s32, 7
	s_lshl_b32 m0, m0, 12
	s_add_i32 m0, m0, 0xc400
	s_nop 0
	global_load_lds_dwordx4 v[160:161], off
	v_mfma_f32_32x32x16_bf16 v[16:31], a[0:3], a[12:15], v[16:31]
	v_mfma_f32_32x32x16_bf16 v[0:15], a[4:7], a[12:15], v[0:15]
	s_and_b32 m0, s32, 7
	s_lshl_b32 m0, m0, 12
	s_add_i32 m0, m0, 0xc800
	s_nop 0
	global_load_lds_dwordx4 v[162:163], off
	s_nop 0
	s_nop 0
	s_nop 0
	s_nop 0
	ds_read_b128 a[0:3], v106
	ds_read_b128 a[4:7], v107
	ds_read_b128 a[8:11], v108
	ds_read_b128 a[12:15], v109
	s_waitcnt lgkmcnt(5)
	v_mfma_f32_32x32x16_bf16 v[48:63], a[16:19], a[24:27], v[48:63]
	v_mfma_f32_32x32x16_bf16 v[32:47], a[20:23], a[24:27], v[32:47]
	s_and_b32 m0, s32, 7
	s_lshl_b32 m0, m0, 12
	s_add_i32 m0, m0, 0xcc00
	s_nop 0
	global_load_lds_dwordx4 v[164:165], off
	s_waitcnt lgkmcnt(4)
	v_mfma_f32_32x32x16_bf16 v[16:31], a[16:19], a[28:31], v[16:31]
	v_mfma_f32_32x32x16_bf16 v[0:15], a[20:23], a[28:31], v[0:15]
	s_and_b32 m0, s32, 7
	s_lshl_b32 m0, m0, 11
	s_add_i32 m0, m0, 0x14000
	s_nop 0
	global_load_lds_dwordx4 v[166:167], off
	s_nop 0
	s_nop 0
	s_nop 0
	s_nop 0
	ds_read_b128 a[16:19], v110
	ds_read_b128 a[20:23], v111
	ds_read_b128 a[24:27], v112
	ds_read_b128 a[28:31], v113
	s_waitcnt lgkmcnt(5)
	v_mfma_f32_32x32x16_bf16 v[48:63], a[0:3], a[8:11], v[48:63]
	v_mfma_f32_32x32x16_bf16 v[32:47], a[4:7], a[8:11], v[32:47]
	s_and_b32 m0, s32, 7
	s_lshl_b32 m0, m0, 11
	s_add_i32 m0, m0, 0x14400
	s_nop 0
	global_load_lds_dwordx4 v[168:169], off
	s_waitcnt lgkmcnt(4)
	v_mfma_f32_32x32x16_bf16 v[16:31], a[0:3], a[12:15], v[16:31]
	v_mfma_f32_32x32x16_bf16 v[0:15], a[4:7], a[12:15], v[0:15]
	s_nop 0
	s_nop 0
	s_nop 0
	s_nop 0
	s_waitcnt lgkmcnt(1)
	v_mfma_f32_32x32x16_bf16 v[48:63], a[16:19], a[24:27], v[48:63]
	v_mfma_f32_32x32x16_bf16 v[32:47], a[20:23], a[24:27], v[32:47]
	s_waitcnt vmcnt(6)
	s_waitcnt lgkmcnt(0)
	s_barrier
	ds_read_b128 a[12:15], v82 offset:4096
	ds_read_b128 a[8:11], v82
	ds_read_b128 a[4:7], v83 offset:36864
	ds_read_b128 a[0:3], v83 offset:32768
	v_mfma_f32_32x32x16_bf16 v[16:31], a[16:19], a[28:31], v[16:31]
	v_lshl_add_u64 v[170:171], v[66:67], 0, s[30:31]
	s_nop 0
	v_lshl_add_u64 v[172:173], v[68:69], 0, s[30:31]
	s_nop 0
	s_nop 0
	s_nop 0
	v_lshl_add_u64 v[174:175], v[70:71], 0, s[30:31]
	s_nop 0
	v_mfma_f32_32x32x16_bf16 v[0:15], a[20:23], a[28:31], v[0:15]
	s_and_b32 m0, s32, 7
	s_lshl_b32 m0, m0, 12
	s_add_i32 m0, m0, 0x18000
	s_nop 0
	global_load_lds_dwordx4 v[170:171], off
	s_nop 0
	v_lshl_add_u64 v[176:177], v[72:73], 0, s[30:31]
	s_nop 0
	s_nop 0
	s_nop 0
	v_lshl_add_u64 v[178:179], v[74:75], 0, s[30:31]
	s_nop 0
	s_nop 0
	s_nop 0
	v_lshl_add_u64 v[180:181], v[76:77], 0, s[30:31]
	s_nop 0
	s_mov_b64 s[30:31], 0x780
	s_nop 0
	s_nop 0
	s_nop 0
	s_nop 0
	s_nop 0
	ds_read_b128 a[16:19], v85 offset:32768
	ds_read_b128 a[20:23], v85 offset:36864
	ds_read_b128 a[24:27], v84
	ds_read_b128 a[28:31], v84 offset:4096
	s_waitcnt lgkmcnt(4)
	v_mfma_f32_32x32x16_bf16 v[48:63], a[0:3], a[8:11], v[48:63]
	v_lshl_add_u64 v[158:159], v[66:67], 0, s[30:31]
	s_nop 0
	v_mfma_f32_32x32x16_bf16 v[32:47], a[4:7], a[8:11], v[32:47]
	s_and_b32 m0, s32, 7
	s_lshl_b32 m0, m0, 12
	s_add_i32 m0, m0, 0x18400
	s_nop 0
	global_load_lds_dwordx4 v[172:173], off
	v_mfma_f32_32x32x16_bf16 v[16:31], a[0:3], a[12:15], v[16:31]
	v_mfma_f32_32x32x16_bf16 v[0:15], a[4:7], a[12:15], v[0:15]
	s_and_b32 m0, s32, 7
	s_lshl_b32 m0, m0, 12
	s_add_i32 m0, m0, 0x18800
	s_nop 0
	global_load_lds_dwordx4 v[174:175], off
	s_nop 0
	s_nop 0
	s_nop 0
	s_nop 0
	ds_read_b128 a[0:3], v87 offset:32768
	ds_read_b128 a[4:7], v87 offset:36864
	ds_read_b128 a[8:11], v86
	ds_read_b128 a[12:15], v86 offset:4096
	s_waitcnt lgkmcnt(5)
	v_mfma_f32_32x32x16_bf16 v[48:63], a[16:19], a[24:27], v[48:63]
	v_mfma_f32_32x32x16_bf16 v[32:47], a[20:23], a[24:27], v[32:47]
	s_and_b32 m0, s32, 7
	s_lshl_b32 m0, m0, 12
	s_add_i32 m0, m0, 0x18c00
	s_nop 0
	global_load_lds_dwordx4 v[176:177], off
	s_waitcnt lgkmcnt(4)
	v_mfma_f32_32x32x16_bf16 v[16:31], a[16:19], a[28:31], v[16:31]
	v_mfma_f32_32x32x16_bf16 v[0:15], a[20:23], a[28:31], v[0:15]
	s_and_b32 m0, s32, 7
	s_lshl_b32 m0, m0, 11
	s_add_i32 m0, m0, 0x20000
	s_nop 0
	global_load_lds_dwordx4 v[178:179], off
	s_nop 0
	s_nop 0
	s_nop 0
	s_nop 0
	ds_read_b128 a[16:19], v89 offset:32768
	ds_read_b128 a[20:23], v89 offset:36864
	ds_read_b128 a[24:27], v88
	ds_read_b128 a[28:31], v88 offset:4096
	s_waitcnt lgkmcnt(5)
	v_mfma_f32_32x32x16_bf16 v[48:63], a[0:3], a[8:11], v[48:63]
	v_mfma_f32_32x32x16_bf16 v[32:47], a[4:7], a[8:11], v[32:47]
	s_and_b32 m0, s32, 7
	s_lshl_b32 m0, m0, 11
	s_add_i32 m0, m0, 0x20400
	s_nop 0
	global_load_lds_dwordx4 v[180:181], off
	s_waitcnt lgkmcnt(4)
	v_mfma_f32_32x32x16_bf16 v[16:31], a[0:3], a[12:15], v[16:31]
	v_mfma_f32_32x32x16_bf16 v[0:15], a[4:7], a[12:15], v[0:15]
	s_nop 0
	s_nop 0
	s_nop 0
	s_nop 0
	s_waitcnt lgkmcnt(1)
	v_mfma_f32_32x32x16_bf16 v[48:63], a[16:19], a[24:27], v[48:63]
	v_mfma_f32_32x32x16_bf16 v[32:47], a[20:23], a[24:27], v[32:47]
	s_waitcnt vmcnt(6)
	s_waitcnt lgkmcnt(0)
	s_barrier
	ds_read_b128 a[12:15], v82 offset:53248
	ds_read_b128 a[8:11], v82 offset:49152
	ds_read_b128 a[4:7], v90
	ds_read_b128 a[0:3], v92
	s_nop 0
	v_lshl_add_u64 v[160:161], v[68:69], 0, s[30:31]
	s_nop 0
	v_mfma_f32_32x32x16_bf16 v[16:31], a[16:19], a[28:31], v[16:31]
	s_nop 0
	v_lshl_add_u64 v[162:163], v[70:71], 0, s[30:31]
	s_nop 0
	v_readlane_b32 s20, v215, 52
	s_nop 0
	v_lshl_add_u64 v[164:165], v[72:73], 0, s[30:31]
	s_nop 0
	v_mfma_f32_32x32x16_bf16 v[0:15], a[20:23], a[28:31], v[0:15]
	s_and_b32 m0, s32, 7
	s_lshl_b32 m0, m0, 12
	s_add_i32 m0, m0, 0x0
	s_nop 0
	global_load_lds_dwordx4 v[158:159], off
	s_nop 0
	v_lshl_add_u64 v[166:167], v[74:75], 0, s[30:31]
	s_nop 0
	v_readlane_b32 s21, v215, 53
	s_nop 0
	v_lshl_add_u64 v[168:169], v[76:77], 0, s[30:31]
	s_nop 0
	s_mov_b32 s23, 0
	s_nop 0
	s_nop 0
	s_nop 0
	s_nop 0
	s_nop 0
	ds_read_b128 a[16:19], v93
	ds_read_b128 a[20:23], v91
	ds_read_b128 a[24:27], v84 offset:49152
	ds_read_b128 a[28:31], v84 offset:53248
	s_waitcnt lgkmcnt(4)
	v_mfma_f32_32x32x16_bf16 v[48:63], a[0:3], a[8:11], v[48:63]
	v_mfma_f32_32x32x16_bf16 v[32:47], a[4:7], a[8:11], v[32:47]
	s_and_b32 m0, s32, 7
	s_lshl_b32 m0, m0, 12
	s_add_i32 m0, m0, 0x400
	s_nop 0
	global_load_lds_dwordx4 v[160:161], off
	v_mfma_f32_32x32x16_bf16 v[16:31], a[0:3], a[12:15], v[16:31]
	v_mfma_f32_32x32x16_bf16 v[0:15], a[4:7], a[12:15], v[0:15]
	s_and_b32 m0, s32, 7
	s_lshl_b32 m0, m0, 12
	s_add_i32 m0, m0, 0x800
	s_nop 0
	global_load_lds_dwordx4 v[162:163], off
	s_nop 0
	s_nop 0
	s_nop 0
	s_nop 0
	ds_read_b128 a[0:3], v95
	ds_read_b128 a[4:7], v94
	ds_read_b128 a[8:11], v86 offset:49152
	ds_read_b128 a[12:15], v86 offset:53248
	s_waitcnt lgkmcnt(5)
	v_mfma_f32_32x32x16_bf16 v[48:63], a[16:19], a[24:27], v[48:63]
	v_mfma_f32_32x32x16_bf16 v[32:47], a[20:23], a[24:27], v[32:47]
	s_and_b32 m0, s32, 7
	s_lshl_b32 m0, m0, 12
	s_add_i32 m0, m0, 0xc00
	s_nop 0
	global_load_lds_dwordx4 v[164:165], off
	s_waitcnt lgkmcnt(4)
	v_mfma_f32_32x32x16_bf16 v[16:31], a[16:19], a[28:31], v[16:31]
	v_mfma_f32_32x32x16_bf16 v[0:15], a[20:23], a[28:31], v[0:15]
	s_and_b32 m0, s32, 7
	s_lshl_b32 m0, m0, 11
	s_add_i32 m0, m0, 0x8000
	s_nop 0
	global_load_lds_dwordx4 v[166:167], off
	s_nop 0
	s_nop 0
	s_nop 0
	s_nop 0
	ds_read_b128 a[16:19], v97
	ds_read_b128 a[20:23], v96
	ds_read_b128 a[24:27], v88 offset:49152
	ds_read_b128 a[28:31], v88 offset:53248
	s_waitcnt lgkmcnt(5)
	v_mfma_f32_32x32x16_bf16 v[48:63], a[0:3], a[8:11], v[48:63]
	v_mfma_f32_32x32x16_bf16 v[32:47], a[4:7], a[8:11], v[32:47]
	s_and_b32 m0, s32, 7
	s_lshl_b32 m0, m0, 11
	s_add_i32 m0, m0, 0x8400
	s_nop 0
	global_load_lds_dwordx4 v[168:169], off
	s_waitcnt lgkmcnt(4)
	v_mfma_f32_32x32x16_bf16 v[16:31], a[0:3], a[12:15], v[16:31]
	v_mfma_f32_32x32x16_bf16 v[0:15], a[4:7], a[12:15], v[0:15]
	s_nop 0
	s_nop 0
	s_nop 0
	s_nop 0
	s_waitcnt lgkmcnt(1)
	v_mfma_f32_32x32x16_bf16 v[48:63], a[16:19], a[24:27], v[48:63]
	v_mfma_f32_32x32x16_bf16 v[32:47], a[20:23], a[24:27], v[32:47]
	s_waitcnt vmcnt(6)
	s_waitcnt lgkmcnt(0)
	s_barrier
	ds_read_b128 a[12:15], v101
	ds_read_b128 a[8:11], v100
	ds_read_b128 a[4:7], v99
	ds_read_b128 a[0:3], v98
	v_mfma_f32_32x32x16_bf16 v[16:31], a[16:19], a[28:31], v[16:31]
	v_mfma_f32_32x32x16_bf16 v[0:15], a[20:23], a[28:31], v[0:15]
	s_nop 0
	s_nop 0
	s_nop 0
	s_nop 0
	ds_read_b128 a[16:19], v102
	ds_read_b128 a[20:23], v103
	ds_read_b128 a[24:27], v104
	ds_read_b128 a[28:31], v105
	s_waitcnt lgkmcnt(4)
	v_mfma_f32_32x32x16_bf16 v[48:63], a[0:3], a[8:11], v[48:63]
	v_mfma_f32_32x32x16_bf16 v[32:47], a[4:7], a[8:11], v[32:47]
	v_mfma_f32_32x32x16_bf16 v[16:31], a[0:3], a[12:15], v[16:31]
	v_mfma_f32_32x32x16_bf16 v[0:15], a[4:7], a[12:15], v[0:15]
	s_nop 0
	s_nop 0
	s_nop 0
	s_nop 0
	ds_read_b128 a[0:3], v106
	ds_read_b128 a[4:7], v107
	ds_read_b128 a[8:11], v108
	ds_read_b128 a[12:15], v109
	s_waitcnt lgkmcnt(5)
	v_mfma_f32_32x32x16_bf16 v[48:63], a[16:19], a[24:27], v[48:63]
	v_mfma_f32_32x32x16_bf16 v[32:47], a[20:23], a[24:27], v[32:47]
	s_waitcnt lgkmcnt(4)
	v_mfma_f32_32x32x16_bf16 v[16:31], a[16:19], a[28:31], v[16:31]
	v_mfma_f32_32x32x16_bf16 v[0:15], a[20:23], a[28:31], v[0:15]
	s_nop 0
	s_nop 0
	s_nop 0
	s_nop 0
	ds_read_b128 a[16:19], v110
	ds_read_b128 a[20:23], v111
	ds_read_b128 a[24:27], v112
	ds_read_b128 a[28:31], v113
	s_waitcnt lgkmcnt(5)
	v_mfma_f32_32x32x16_bf16 v[48:63], a[0:3], a[8:11], v[48:63]
	v_mfma_f32_32x32x16_bf16 v[32:47], a[4:7], a[8:11], v[32:47]
	s_waitcnt lgkmcnt(4)
	v_mfma_f32_32x32x16_bf16 v[16:31], a[0:3], a[12:15], v[16:31]
	v_mfma_f32_32x32x16_bf16 v[0:15], a[4:7], a[12:15], v[0:15]
	s_nop 0
	s_nop 0
	s_nop 0
	s_nop 0
	s_waitcnt lgkmcnt(1)
	v_mfma_f32_32x32x16_bf16 v[48:63], a[16:19], a[24:27], v[48:63]
	v_mfma_f32_32x32x16_bf16 v[32:47], a[20:23], a[24:27], v[32:47]
	s_waitcnt vmcnt(0)
	s_waitcnt lgkmcnt(0)
	s_barrier
	ds_read_b128 a[12:15], v82 offset:4096
	ds_read_b128 a[8:11], v82
	ds_read_b128 a[4:7], v83 offset:36864
	ds_read_b128 a[0:3], v83 offset:32768
	v_mfma_f32_32x32x16_bf16 v[16:31], a[16:19], a[28:31], v[16:31]
	v_mfma_f32_32x32x16_bf16 v[0:15], a[20:23], a[28:31], v[0:15]
	s_nop 0
	s_nop 0
	s_nop 0
	s_nop 0
	ds_read_b128 a[16:19], v85 offset:32768
	ds_read_b128 a[20:23], v85 offset:36864
	ds_read_b128 a[24:27], v84
	ds_read_b128 a[28:31], v84 offset:4096
	s_waitcnt lgkmcnt(4)
	v_mfma_f32_32x32x16_bf16 v[48:63], a[0:3], a[8:11], v[48:63]
	v_mfma_f32_32x32x16_bf16 v[32:47], a[4:7], a[8:11], v[32:47]
	v_mfma_f32_32x32x16_bf16 v[16:31], a[0:3], a[12:15], v[16:31]
	v_mfma_f32_32x32x16_bf16 v[0:15], a[4:7], a[12:15], v[0:15]
	s_nop 0
	s_nop 0
	s_nop 0
	s_nop 0
	ds_read_b128 a[0:3], v87 offset:32768
	ds_read_b128 a[4:7], v87 offset:36864
	ds_read_b128 a[8:11], v86
	ds_read_b128 a[12:15], v86 offset:4096
	s_waitcnt lgkmcnt(5)
	v_mfma_f32_32x32x16_bf16 v[48:63], a[16:19], a[24:27], v[48:63]
	v_mfma_f32_32x32x16_bf16 v[32:47], a[20:23], a[24:27], v[32:47]
	s_waitcnt lgkmcnt(4)
	v_mfma_f32_32x32x16_bf16 v[16:31], a[16:19], a[28:31], v[16:31]
	v_mfma_f32_32x32x16_bf16 v[0:15], a[20:23], a[28:31], v[0:15]
	s_nop 0
	s_nop 0
	s_nop 0
	s_waitcnt lgkmcnt(1)
	v_mfma_f32_32x32x16_bf16 v[48:63], a[0:3], a[8:11], v[48:63]
	v_mfma_f32_32x32x16_bf16 v[32:47], a[4:7], a[8:11], v[32:47]
	s_nop 0
	s_waitcnt lgkmcnt(0)
	v_mfma_f32_32x32x16_bf16 v[0:15], a[4:7], a[12:15], v[0:15]
	v_mfma_f32_32x32x16_bf16 v[16:31], a[0:3], a[12:15], v[16:31]
	ds_read_b128 v[66:69], v89 offset:32768
	ds_read_b128 v[70:73], v88
	ds_read_b128 v[74:77], v89 offset:36864
	ds_read_b128 v[82:85], v88 offset:4096
	s_waitcnt lgkmcnt(0)
	s_barrier
	s_waitcnt lgkmcnt(0)
	v_mfma_f32_32x32x16_bf16 v[48:63], v[66:69], v[70:73], v[48:63]
	v_mfma_f32_32x32x16_bf16 v[32:47], v[74:77], v[70:73], v[32:47]
	s_nop 10
	ds_write_b128 v64, v[48:51]
	ds_write_b128 v64, v[52:55] offset:32
	ds_write_b128 v64, v[56:59] offset:64
	ds_write_b128 v64, v[60:63] offset:96
	ds_write_b128 v64, v[32:35] offset:128
	v_mfma_f32_32x32x16_bf16 v[0:15], v[74:77], v[82:85], v[0:15]
	v_mfma_f32_32x32x16_bf16 v[16:31], v[66:69], v[82:85], v[16:31]
	ds_write_b128 v64, v[36:39] offset:160
	ds_write_b128 v64, v[40:43] offset:192
	ds_write_b128 v64, v[44:47] offset:224
	s_nop 8
	ds_write_b128 v64, v[16:19] offset:16896
	ds_write_b128 v64, v[20:23] offset:16928
	ds_write_b128 v64, v[24:27] offset:16960
	ds_write_b128 v64, v[28:31] offset:16992
	ds_write_b128 v64, v[0:3] offset:17024
	ds_write_b128 v64, v[4:7] offset:17056
	ds_write_b128 v64, v[8:11] offset:17088
	ds_write_b128 v64, v[12:15] offset:17120
	s_waitcnt lgkmcnt(0)
	s_barrier
	v_lshl_or_b32 v0, v79, 2, s0
	v_ashrrev_i32_e32 v1, 31, v0
	v_lshl_add_u32 v4, v79, 4, 0
	v_cmp_eq_u32_e64 s[0:1], 0, v79
	v_lshl_add_u64 v[6:7], v[0:1], 2, s[92:93]
	v_lshl_add_u64 v[8:9], v[0:1], 1, s[20:21]
	s_branch .LBB0_96

.LBB0_159:
	v_mov_b32_e32 v78, v133
	s_lshl_b32 s22, s2, 8
	v_ashrrev_i32_e32 v6, 6, v78
	v_bfe_u32 v7, v78, 3, 3
	v_lshl_or_b32 v8, v6, 5, v7
	v_add_u32_e32 v0, s22, v8
	s_waitcnt lgkmcnt(0)
	v_ashrrev_i32_e32 v1, 31, v0
	v_lshlrev_b64 v[2:3], 11, v[0:1]
	v_bfe_u32 v1, v78, 4, 2
	v_readlane_b32 s0, v214, 4
	v_xor_b32_e32 v1, v1, v78
	v_readlane_b32 s1, v214, 5
	v_lshlrev_b32_e32 v1, 4, v1
	v_and_b32_e32 v64, 0x70, v1
	v_lshl_add_u64 v[2:3], s[0:1], 0, v[2:3]
	v_or_b32_e32 v1, 8, v8
	v_lshl_add_u64 v[66:67], v[2:3], 0, v[64:65]
	v_add_u32_e32 v2, s22, v1
	v_lshrrev_b32_e32 v1, 1, v1
	v_xor_b32_e32 v1, v1, v78
	v_ashrrev_i32_e32 v3, 31, v2
	v_lshlrev_b32_e32 v1, 4, v1
	v_or_b32_e32 v0, 16, v0
	v_lshlrev_b64 v[2:3], 11, v[2:3]
	v_and_b32_e32 v4, 0x70, v1
	v_ashrrev_i32_e32 v1, 31, v0
	v_lshl_add_u64 v[2:3], s[0:1], 0, v[2:3]
	v_mov_b32_e32 v5, v65
	v_lshlrev_b64 v[0:1], 11, v[0:1]
	v_lshl_add_u64 v[68:69], v[2:3], 0, v[4:5]
	v_lshl_add_u64 v[0:1], s[0:1], 0, v[0:1]
	v_or_b32_e32 v2, 24, v8
	v_lshl_add_u64 v[70:71], v[0:1], 0, v[64:65]
	v_add_u32_e32 v0, s22, v2
	v_lshrrev_b32_e32 v2, 1, v2
	v_ashrrev_i32_e32 v1, 31, v0
	v_xor_b32_e32 v2, v2, v78
	v_lshlrev_b64 v[0:1], 11, v[0:1]
	v_lshlrev_b32_e32 v2, 4, v2
	v_lshl_add_u64 v[0:1], s[0:1], 0, v[0:1]
	v_and_b32_e32 v2, 0x70, v2
	v_mov_b32_e32 v3, v65
	v_lshl_add_u64 v[72:73], v[0:1], 0, v[2:3]
	v_lshl_or_b32 v2, v6, 4, v7
	v_readlane_b32 s31, v214, 58
	v_lshlrev_b32_e32 v3, 12, v6
	v_add_u32_e32 v126, 0, v3
	v_add_u32_e32 v0, s31, v2
	v_ashrrev_i32_e32 v1, 31, v0
	v_lshlrev_b64 v[0:1], 11, v[0:1]
	s_nop 0
	v_readfirstlane_b32 s37, v126
	v_add_u32_e32 v127, 0x400, v126
	v_lshl_add_u64 v[0:1], s[40:41], 0, v[0:1]
	v_or_b32_e32 v2, 8, v2
	s_waitcnt lgkmcnt(0)
	s_barrier
	s_mov_b32 m0, s37
	v_readfirstlane_b32 s38, v127
	v_add_u32_e32 v128, 0x800, v126
	v_lshlrev_b32_e32 v5, 11, v6
	v_and_b32_e32 v80, 1, v6
	v_lshl_add_u64 v[74:75], v[0:1], 0, v[64:65]
	v_add_u32_e32 v0, s31, v2
	v_lshrrev_b32_e32 v2, 1, v2
	global_load_lds_dwordx4 v[66:67], off
	s_mov_b32 m0, s38
	v_readfirstlane_b32 s39, v128
	v_add_u32_e32 v129, 0xc00, v126
	v_add_u32_e32 v6, 0, v5
	v_ashrrev_i32_e32 v1, 31, v0
	v_xor_b32_e32 v2, v2, v78
	global_load_lds_dwordx4 v[68:69], off
	s_mov_b32 m0, s39
	v_readfirstlane_b32 s48, v129
	v_add_u32_e32 v131, 0x8000, v6
	v_lshlrev_b64 v[0:1], 11, v[0:1]
	v_lshlrev_b32_e32 v2, 4, v2
	global_load_lds_dwordx4 v[70:71], off
	s_mov_b32 m0, s48
	v_readfirstlane_b32 s49, v131
	v_add_u32_e32 v130, 0x8400, v6
	v_lshl_add_u64 v[0:1], s[40:41], 0, v[0:1]
	v_and_b32_e32 v64, 0x70, v2
	global_load_lds_dwordx4 v[72:73], off
	s_mov_b32 m0, s49
	v_readfirstlane_b32 s53, v130
	v_add_u32_e32 v120, 0xc000, v126
	v_lshl_add_u64 v[76:77], v[0:1], 0, v[64:65]
	global_load_lds_dwordx4 v[74:75], off
	s_mov_b32 m0, s53
	s_mov_b64 s[0:1], 0x80
	v_readfirstlane_b32 s28, v120
	v_add_u32_e32 v121, 0xc400, v126
	global_load_lds_dwordx4 v[76:77], off
	v_lshl_add_u64 v[0:1], v[66:67], 0, s[0:1]
	s_mov_b32 m0, s28
	v_readfirstlane_b32 s29, v121
	v_add_u32_e32 v122, 0xc800, v126
	global_load_lds_dwordx4 v[0:1], off
	v_lshl_add_u64 v[0:1], v[68:69], 0, s[0:1]
	s_mov_b32 m0, s29
	v_readfirstlane_b32 s33, v122
	v_add_u32_e32 v123, 0xcc00, v126
	global_load_lds_dwordx4 v[0:1], off
	v_lshl_add_u64 v[0:1], v[70:71], 0, s[0:1]
	s_mov_b32 m0, s33
	v_readfirstlane_b32 s34, v123
	v_add_u32_e32 v124, s85, v5
	global_load_lds_dwordx4 v[0:1], off
	v_lshl_add_u64 v[0:1], v[72:73], 0, s[0:1]
	s_mov_b32 m0, s34
	v_readfirstlane_b32 s35, v124
	v_add_u32_e32 v125, 0x14400, v6
	global_load_lds_dwordx4 v[0:1], off
	v_lshl_add_u64 v[0:1], v[74:75], 0, s[0:1]
	s_mov_b32 m0, s35
	v_readfirstlane_b32 s36, v125
	global_load_lds_dwordx4 v[0:1], off
	v_lshl_add_u64 v[0:1], v[76:77], 0, s[0:1]
	s_mov_b32 m0, s36
	v_lshrrev_b32_e32 v2, 1, v78
	v_bfe_u32 v64, v78, 5, 1
	global_load_lds_dwordx4 v[0:1], off
	v_add_u32_e32 v114, s3, v3
	v_bitop3_b32 v0, v2, v64, 7 bitop3:0x6c
	s_waitcnt vmcnt(6)
	s_mov_b64 s[46:47], 0x100
	v_readfirstlane_b32 s0, v114
	v_add_u32_e32 v115, 0x400, v114
	v_lshlrev_b32_e32 v132, 4, v0
	s_waitcnt lgkmcnt(0)
	s_barrier
	v_lshl_add_u64 v[0:1], v[66:67], 0, s[46:47]
	s_mov_b32 m0, s0
	v_readfirstlane_b32 s1, v115
	v_add_u32_e32 v116, 0x800, v114
	global_load_lds_dwordx4 v[0:1], off
	v_lshl_add_u64 v[0:1], v[68:69], 0, s[46:47]
	s_mov_b32 m0, s1
	v_readfirstlane_b32 s20, v116
	v_add_u32_e32 v117, 0xc00, v114
	v_readlane_b32 s23, v212, 31
	v_and_b32_e32 v79, 31, v78
	global_load_lds_dwordx4 v[0:1], off
	v_lshl_add_u64 v[0:1], v[70:71], 0, s[46:47]
	s_mov_b32 m0, s20
	v_readfirstlane_b32 s21, v117
	v_add_u32_e32 v118, s23, v5
	v_add_u32_e32 v2, s3, v5
	v_lshlrev_b32_e32 v4, 7, v79
	global_load_lds_dwordx4 v[0:1], off
	v_lshl_add_u64 v[0:1], v[72:73], 0, s[46:47]
	s_mov_b32 m0, s21
	v_readfirstlane_b32 s23, v118
	v_add_u32_e32 v119, 0x8400, v2
	v_lshl_or_b32 v102, v80, 13, v4
	global_load_lds_dwordx4 v[0:1], off
	v_lshl_add_u64 v[0:1], v[74:75], 0, s[46:47]
	s_mov_b32 m0, s23
	v_readfirstlane_b32 s24, v119
	global_load_lds_dwordx4 v[0:1], off
	v_lshl_add_u64 v[0:1], v[76:77], 0, s[46:47]
	s_mov_b32 m0, s24
	v_add_u32_e32 v100, 0, v102
	global_load_lds_dwordx4 v[0:1], off
	v_add_u32_e32 v83, v100, v132
	v_ashrrev_i32_e32 v81, 7, v78
	ds_read_b128 a[0:3], v83 offset:32768
	ds_read_b128 a[4:7], v83 offset:36864
	v_lshl_or_b32 v134, v81, 13, v4
	v_add_u32_e32 v101, 0, v134
	v_add_u32_e32 v82, v101, v132
	ds_read_b128 a[8:11], v82
	ds_read_b128 a[12:15], v82 offset:4096
	v_lshrrev_b32_e32 v182, 6, v133
	s_nop 0
	v_readfirstlane_b32 s32, v182
	s_waitcnt lgkmcnt(1)
	v_mfma_f32_32x32x16_bf16 v[48:63], a[0:3], a[8:11], 0
	v_bfe_u32 v103, v78, 1, 3
	s_mov_b64 s[46:47], 0x180
	s_nop 0
	s_add_i32 s30, 0, 0xc000
	v_or_b32_e32 v143, 0x8000, v102
	v_or_b32_e32 v144, 0x9000, v102
	v_add_u32_e32 v145, s3, v134
	s_waitcnt vmcnt(12)
	v_mfma_f32_32x32x16_bf16 v[32:47], a[4:7], a[8:11], 0
	v_lshl_or_b32 v81, v81, 6, v79
	v_mul_lo_u32 v81, v81, s26
	s_mov_b64 s[80:81], 0x200
	s_waitcnt lgkmcnt(0)
	v_mfma_f32_32x32x16_bf16 v[16:31], a[0:3], a[12:15], 0
	v_bitop3_b32 v0, v64, v103, 2 bitop3:0x36
	v_lshlrev_b32_e32 v138, 4, v0
	v_add_u32_e32 v84, v101, v138
	ds_read_b128 a[28:31], v84 offset:4096
	s_nop 0
	s_nop 0
	ds_read_b128 a[24:27], v84
	s_nop 0
	v_add_u32_e32 v85, v100, v138
	ds_read_b128 a[20:23], v85 offset:36864
	s_nop 0
	s_nop 0
	ds_read_b128 a[16:19], v85 offset:32768
	s_nop 0
	s_nop 0
	s_nop 0
	s_nop 0
	s_nop 0
	s_nop 0
	v_mfma_f32_32x32x16_bf16 v[0:15], a[4:7], a[12:15], 0
	s_nop 0
	s_waitcnt lgkmcnt(0)
	v_mfma_f32_32x32x16_bf16 v[48:63], a[16:19], a[24:27], v[48:63]
	v_mfma_f32_32x32x16_bf16 v[32:47], a[20:23], a[24:27], v[32:47]
	v_mfma_f32_32x32x16_bf16 v[16:31], a[16:19], a[28:31], v[16:31]
	v_bitop3_b32 v86, v64, v103, 4 bitop3:0x36
	v_lshlrev_b32_e32 v139, 4, v86
	v_add_u32_e32 v86, v101, v139
	ds_read_b128 a[12:15], v86 offset:4096
	s_nop 0
	s_nop 0
	ds_read_b128 a[8:11], v86
	s_nop 0
	v_add_u32_e32 v87, v100, v139
	ds_read_b128 a[4:7], v87 offset:36864
	s_nop 0
	s_nop 0
	ds_read_b128 a[0:3], v87 offset:32768
	s_nop 0
	s_nop 0
	s_nop 0
	v_mfma_f32_32x32x16_bf16 v[0:15], a[20:23], a[28:31], v[0:15]
	s_nop 0
	s_nop 0
	s_nop 0
	s_nop 0
	s_waitcnt lgkmcnt(0)
	v_mfma_f32_32x32x16_bf16 v[48:63], a[0:3], a[8:11], v[48:63]
	v_mfma_f32_32x32x16_bf16 v[32:47], a[4:7], a[8:11], v[32:47]
	v_mfma_f32_32x32x16_bf16 v[16:31], a[0:3], a[12:15], v[16:31]
	v_bitop3_b32 v88, v64, v103, 6 bitop3:0x36
	v_lshlrev_b32_e32 v142, 4, v88
	v_add_u32_e32 v88, v101, v142
	ds_read_b128 a[28:31], v88 offset:4096
	s_nop 0
	s_nop 0
	ds_read_b128 a[24:27], v88
	s_nop 0
	v_add_u32_e32 v89, v100, v142
	ds_read_b128 a[20:23], v89 offset:36864
	s_nop 0
	s_nop 0
	ds_read_b128 a[16:19], v89 offset:32768
	s_nop 0
	s_nop 0
	s_nop 0
	v_lshlrev_b32_e32 v64, 4, v64
	v_lshl_or_b32 v64, v80, 8, v64
	v_add3_u32 v64, 0, v81, v64
	v_mfma_f32_32x32x16_bf16 v[0:15], a[4:7], a[12:15], v[0:15]
	s_nop 0
	s_nop 0
	s_nop 0
	s_nop 0
	s_waitcnt lgkmcnt(0)
	v_mfma_f32_32x32x16_bf16 v[48:63], a[16:19], a[24:27], v[48:63]
	v_mfma_f32_32x32x16_bf16 v[32:47], a[20:23], a[24:27], v[32:47]
	s_waitcnt vmcnt(6)
	s_waitcnt lgkmcnt(0)
	s_barrier
	ds_read_b128 a[12:15], v82 offset:53248
	ds_read_b128 a[8:11], v82 offset:49152
	v_add_u32_e32 v90, s30, v132
	v_add_u32_e32 v92, v90, v143
	v_add_u32_e32 v90, v90, v144
	ds_read_b128 a[4:7], v90
	ds_read_b128 a[0:3], v92
	v_mfma_f32_32x32x16_bf16 v[16:31], a[16:19], a[28:31], v[16:31]
	v_lshl_add_u64 v[158:159], v[66:67], 0, s[46:47]
	s_nop 0
	v_lshl_add_u64 v[160:161], v[68:69], 0, s[46:47]
	s_nop 0
	s_nop 0
	s_nop 0
	v_lshl_add_u64 v[162:163], v[70:71], 0, s[46:47]
	s_nop 0
	v_mfma_f32_32x32x16_bf16 v[0:15], a[20:23], a[28:31], v[0:15]
	s_and_b32 m0, s32, 7
	s_lshl_b32 m0, m0, 12
	s_add_i32 m0, m0, 0x0
	s_nop 0
	global_load_lds_dwordx4 v[158:159], off
	s_nop 0
	v_lshl_add_u64 v[164:165], v[72:73], 0, s[46:47]
	s_nop 0
	s_nop 0
	s_nop 0
	v_lshl_add_u64 v[166:167], v[74:75], 0, s[46:47]
	s_nop 0
	s_nop 0
	s_nop 0
	v_lshl_add_u64 v[168:169], v[76:77], 0, s[46:47]
	s_nop 0
	s_mov_b64 s[46:47], 0x200
	s_nop 0
	s_nop 0
	s_nop 0
	s_nop 0
	s_nop 0
	s_nop 0
	s_nop 0
	s_nop 0
	v_add_u32_e32 v91, s30, v138
	v_add_u32_e32 v93, v91, v143
	ds_read_b128 a[16:19], v93
	v_add_u32_e32 v91, v91, v144
	ds_read_b128 a[20:23], v91
	ds_read_b128 a[24:27], v84 offset:49152
	ds_read_b128 a[28:31], v84 offset:53248
	s_waitcnt lgkmcnt(4)
	v_mfma_f32_32x32x16_bf16 v[48:63], a[0:3], a[8:11], v[48:63]
	s_nop 0
	s_nop 0
	s_nop 0
	s_nop 0
	v_mfma_f32_32x32x16_bf16 v[32:47], a[4:7], a[8:11], v[32:47]
	s_and_b32 m0, s32, 7
	s_lshl_b32 m0, m0, 12
	s_add_i32 m0, m0, 0x400
	s_nop 0
	global_load_lds_dwordx4 v[160:161], off
	v_mfma_f32_32x32x16_bf16 v[16:31], a[0:3], a[12:15], v[16:31]
	v_mfma_f32_32x32x16_bf16 v[0:15], a[4:7], a[12:15], v[0:15]
	s_and_b32 m0, s32, 7
	s_lshl_b32 m0, m0, 12
	s_add_i32 m0, m0, 0x800
	s_nop 0
	global_load_lds_dwordx4 v[162:163], off
	s_nop 0
	s_nop 0
	s_nop 0
	s_nop 0
	v_add_u32_e32 v94, s30, v139
	v_add_u32_e32 v95, v94, v143
	ds_read_b128 a[0:3], v95
	v_add_u32_e32 v94, v94, v144
	ds_read_b128 a[4:7], v94
	ds_read_b128 a[8:11], v86 offset:49152
	ds_read_b128 a[12:15], v86 offset:53248
	s_waitcnt lgkmcnt(5)
	v_mfma_f32_32x32x16_bf16 v[48:63], a[16:19], a[24:27], v[48:63]
	v_mfma_f32_32x32x16_bf16 v[32:47], a[20:23], a[24:27], v[32:47]
	s_and_b32 m0, s32, 7
	s_lshl_b32 m0, m0, 12
	s_add_i32 m0, m0, 0xc00
	s_nop 0
	global_load_lds_dwordx4 v[164:165], off
	s_waitcnt lgkmcnt(4)
	v_mfma_f32_32x32x16_bf16 v[16:31], a[16:19], a[28:31], v[16:31]
	s_nop 0
	s_nop 0
	s_nop 0
	v_mfma_f32_32x32x16_bf16 v[0:15], a[20:23], a[28:31], v[0:15]
	s_and_b32 m0, s32, 7
	s_lshl_b32 m0, m0, 11
	s_add_i32 m0, m0, 0x8000
	s_nop 0
	global_load_lds_dwordx4 v[166:167], off
	s_nop 0
	s_nop 0
	s_nop 0
	s_nop 0
	v_add_u32_e32 v96, s30, v142
	v_add_u32_e32 v97, v96, v143
	ds_read_b128 a[16:19], v97
	v_add_u32_e32 v96, v96, v144
	ds_read_b128 a[20:23], v96
	ds_read_b128 a[24:27], v88 offset:49152
	ds_read_b128 a[28:31], v88 offset:53248
	s_waitcnt lgkmcnt(5)
	v_mfma_f32_32x32x16_bf16 v[48:63], a[0:3], a[8:11], v[48:63]
	v_mfma_f32_32x32x16_bf16 v[32:47], a[4:7], a[8:11], v[32:47]
	s_and_b32 m0, s32, 7
	s_lshl_b32 m0, m0, 11
	s_add_i32 m0, m0, 0x8400
	s_nop 0
	global_load_lds_dwordx4 v[168:169], off
	s_waitcnt lgkmcnt(4)
	v_mfma_f32_32x32x16_bf16 v[16:31], a[0:3], a[12:15], v[16:31]
	s_nop 0
	s_nop 0
	s_nop 0
	v_mfma_f32_32x32x16_bf16 v[0:15], a[4:7], a[12:15], v[0:15]
	s_nop 0
	s_nop 0
	s_nop 0
	s_nop 0
	s_waitcnt lgkmcnt(1)
	v_mfma_f32_32x32x16_bf16 v[48:63], a[16:19], a[24:27], v[48:63]
	v_mfma_f32_32x32x16_bf16 v[32:47], a[20:23], a[24:27], v[32:47]
	s_waitcnt vmcnt(6)
	s_waitcnt lgkmcnt(0)
	s_barrier
	v_add_u32_e32 v100, v145, v132
	ds_read_b128 a[8:11], v100
	v_add_u32_e32 v101, s3, v132
	v_add_u32_e32 v99, v101, v144
	ds_read_b128 a[4:7], v99
	s_nop 0
	v_add_u32_e32 v98, v101, v143
	v_or_b32_e32 v132, 0x1000, v134
	v_add_u32_e32 v101, v101, v132
	ds_read_b128 a[12:15], v101
	ds_read_b128 a[0:3], v98
	v_mfma_f32_32x32x16_bf16 v[16:31], a[16:19], a[28:31], v[16:31]
	v_lshl_add_u64 v[170:171], v[66:67], 0, s[46:47]
	s_nop 0
	v_lshl_add_u64 v[172:173], v[68:69], 0, s[46:47]
	s_nop 0
	s_nop 0
	s_nop 0
	v_lshl_add_u64 v[174:175], v[70:71], 0, s[46:47]
	s_nop 0
	v_mfma_f32_32x32x16_bf16 v[0:15], a[20:23], a[28:31], v[0:15]
	s_and_b32 m0, s32, 7
	s_lshl_b32 m0, m0, 12
	s_add_i32 m0, m0, 0xc000
	s_nop 0
	global_load_lds_dwordx4 v[170:171], off
	s_nop 0
	v_lshl_add_u64 v[176:177], v[72:73], 0, s[46:47]
	s_nop 0
	s_nop 0
	s_nop 0
	v_lshl_add_u64 v[178:179], v[74:75], 0, s[46:47]
	s_nop 0
	s_nop 0
	s_nop 0
	v_lshl_add_u64 v[180:181], v[76:77], 0, s[46:47]
	s_nop 0
	s_mov_b64 s[46:47], 0x280
	s_nop 0
	s_nop 0
	s_nop 0
	s_nop 0
	s_nop 0
	s_nop 0
	s_nop 0
	s_nop 0
	v_add_u32_e32 v105, s3, v138
	v_add_u32_e32 v102, v105, v143
	ds_read_b128 a[16:19], v102
	v_add_u32_e32 v103, v105, v144
	ds_read_b128 a[20:23], v103
	v_add_u32_e32 v104, v145, v138
	ds_read_b128 a[24:27], v104
	v_add_u32_e32 v105, v105, v132
	ds_read_b128 a[28:31], v105
	s_waitcnt lgkmcnt(4)
	v_mfma_f32_32x32x16_bf16 v[48:63], a[0:3], a[8:11], v[48:63]
	s_nop 0
	v_mfma_f32_32x32x16_bf16 v[32:47], a[4:7], a[8:11], v[32:47]
	s_and_b32 m0, s32, 7
	s_lshl_b32 m0, m0, 12
	s_add_i32 m0, m0, 0xc400
	s_nop 0
	global_load_lds_dwordx4 v[172:173], off
	s_nop 0
	s_nop 0
	s_nop 0
	s_nop 0
	s_nop 0
	v_mfma_f32_32x32x16_bf16 v[16:31], a[0:3], a[12:15], v[16:31]
	s_nop 0
	v_mfma_f32_32x32x16_bf16 v[0:15], a[4:7], a[12:15], v[0:15]
	s_and_b32 m0, s32, 7
	s_lshl_b32 m0, m0, 12
	s_add_i32 m0, m0, 0xc800
	s_nop 0
	global_load_lds_dwordx4 v[174:175], off
	s_nop 0
	s_nop 0
	s_nop 0
	v_add_u32_e32 v109, s3, v139
	v_add_u32_e32 v106, v109, v143
	ds_read_b128 a[0:3], v106
	v_add_u32_e32 v107, v109, v144
	ds_read_b128 a[4:7], v107
	v_add_u32_e32 v108, v145, v139
	ds_read_b128 a[8:11], v108
	v_add_u32_e32 v109, v109, v132
	ds_read_b128 a[12:15], v109
	s_waitcnt lgkmcnt(5)
	v_mfma_f32_32x32x16_bf16 v[48:63], a[16:19], a[24:27], v[48:63]
	v_mfma_f32_32x32x16_bf16 v[32:47], a[20:23], a[24:27], v[32:47]
	s_and_b32 m0, s32, 7
	s_lshl_b32 m0, m0, 12
	s_add_i32 m0, m0, 0xcc00
	s_nop 0
	global_load_lds_dwordx4 v[176:177], off
	s_waitcnt lgkmcnt(4)
	v_mfma_f32_32x32x16_bf16 v[16:31], a[16:19], a[28:31], v[16:31]
	s_nop 0
	s_nop 0
	s_nop 0
	s_nop 0
	s_nop 0
	s_nop 0
	v_mfma_f32_32x32x16_bf16 v[0:15], a[20:23], a[28:31], v[0:15]
	s_and_b32 m0, s32, 7
	s_lshl_b32 m0, m0, 11
	s_add_i32 m0, m0, 0x14000
	s_nop 0
	global_load_lds_dwordx4 v[178:179], off
	s_nop 0
	s_nop 0
	s_nop 0
	v_add_u32_e32 v113, s3, v142
	v_add_u32_e32 v110, v113, v143
	ds_read_b128 a[16:19], v110
	v_add_u32_e32 v111, v113, v144
	ds_read_b128 a[20:23], v111
	v_add_u32_e32 v112, v145, v142
	ds_read_b128 a[24:27], v112
	v_add_u32_e32 v113, v113, v132
	ds_read_b128 a[28:31], v113
	s_waitcnt lgkmcnt(5)
	v_mfma_f32_32x32x16_bf16 v[48:63], a[0:3], a[8:11], v[48:63]
	v_mfma_f32_32x32x16_bf16 v[32:47], a[4:7], a[8:11], v[32:47]
	s_and_b32 m0, s32, 7
	s_lshl_b32 m0, m0, 11
	s_add_i32 m0, m0, 0x14400
	s_nop 0
	global_load_lds_dwordx4 v[180:181], off
	s_waitcnt lgkmcnt(4)
	v_mfma_f32_32x32x16_bf16 v[16:31], a[0:3], a[12:15], v[16:31]
	s_nop 0
	s_nop 0
	s_nop 0
	s_nop 0
	s_nop 0
	s_nop 0
	v_mfma_f32_32x32x16_bf16 v[0:15], a[4:7], a[12:15], v[0:15]
	s_nop 0
	s_nop 0
	s_nop 0
	s_waitcnt lgkmcnt(1)
	v_mfma_f32_32x32x16_bf16 v[48:63], a[16:19], a[24:27], v[48:63]
	v_mfma_f32_32x32x16_bf16 v[32:47], a[20:23], a[24:27], v[32:47]
	s_waitcnt vmcnt(6)
	s_waitcnt lgkmcnt(0)
	s_barrier
	ds_read_b128 a[12:15], v82 offset:4096
	ds_read_b128 a[8:11], v82
	ds_read_b128 a[4:7], v83 offset:36864
	ds_read_b128 a[0:3], v83 offset:32768
	v_mfma_f32_32x32x16_bf16 v[16:31], a[16:19], a[28:31], v[16:31]
	v_lshl_add_u64 v[158:159], v[66:67], 0, s[46:47]
	s_nop 0
	v_lshl_add_u64 v[160:161], v[68:69], 0, s[46:47]
	s_nop 0
	s_nop 0
	s_nop 0
	v_lshl_add_u64 v[162:163], v[70:71], 0, s[46:47]
	s_nop 0
	v_mfma_f32_32x32x16_bf16 v[0:15], a[20:23], a[28:31], v[0:15]
	s_and_b32 m0, s32, 7
	s_lshl_b32 m0, m0, 12
	s_add_i32 m0, m0, 0x18000
	s_nop 0
	global_load_lds_dwordx4 v[158:159], off
	s_nop 0
	v_lshl_add_u64 v[164:165], v[72:73], 0, s[46:47]
	s_nop 0
	s_nop 0
	s_nop 0
	v_lshl_add_u64 v[166:167], v[74:75], 0, s[46:47]
	s_nop 0
	s_nop 0
	s_nop 0
	v_lshl_add_u64 v[168:169], v[76:77], 0, s[46:47]
	s_nop 0
	s_mov_b64 s[46:47], 0x300
	s_nop 0
	s_nop 0
	s_nop 0
	s_nop 0
	s_nop 0
	ds_read_b128 a[16:19], v85 offset:32768
	ds_read_b128 a[20:23], v85 offset:36864
	ds_read_b128 a[24:27], v84
	ds_read_b128 a[28:31], v84 offset:4096
	s_waitcnt lgkmcnt(4)
	v_mfma_f32_32x32x16_bf16 v[48:63], a[0:3], a[8:11], v[48:63]
	s_nop 0
	v_mfma_f32_32x32x16_bf16 v[32:47], a[4:7], a[8:11], v[32:47]
	s_and_b32 m0, s32, 7
	s_lshl_b32 m0, m0, 12
	s_add_i32 m0, m0, 0x18400
	s_nop 0
	global_load_lds_dwordx4 v[160:161], off
	v_mfma_f32_32x32x16_bf16 v[16:31], a[0:3], a[12:15], v[16:31]
	v_mfma_f32_32x32x16_bf16 v[0:15], a[4:7], a[12:15], v[0:15]
	s_and_b32 m0, s32, 7
	s_lshl_b32 m0, m0, 12
	s_add_i32 m0, m0, 0x18800
	s_nop 0
	global_load_lds_dwordx4 v[162:163], off
	s_nop 0
	s_nop 0
	s_nop 0
	s_nop 0
	ds_read_b128 a[0:3], v87 offset:32768
	ds_read_b128 a[4:7], v87 offset:36864
	ds_read_b128 a[8:11], v86
	ds_read_b128 a[12:15], v86 offset:4096
	s_waitcnt lgkmcnt(5)
	v_mfma_f32_32x32x16_bf16 v[48:63], a[16:19], a[24:27], v[48:63]
	v_mfma_f32_32x32x16_bf16 v[32:47], a[20:23], a[24:27], v[32:47]
	s_and_b32 m0, s32, 7
	s_lshl_b32 m0, m0, 12
	s_add_i32 m0, m0, 0x18c00
	s_nop 0
	global_load_lds_dwordx4 v[164:165], off
	s_waitcnt lgkmcnt(4)
	v_mfma_f32_32x32x16_bf16 v[16:31], a[16:19], a[28:31], v[16:31]
	v_mfma_f32_32x32x16_bf16 v[0:15], a[20:23], a[28:31], v[0:15]
	s_and_b32 m0, s32, 7
	s_lshl_b32 m0, m0, 11
	s_add_i32 m0, m0, 0x20000
	s_nop 0
	global_load_lds_dwordx4 v[166:167], off
	s_nop 0
	s_nop 0
	s_nop 0
	s_nop 0
	ds_read_b128 a[16:19], v89 offset:32768
	ds_read_b128 a[20:23], v89 offset:36864
	ds_read_b128 a[24:27], v88
	ds_read_b128 a[28:31], v88 offset:4096
	s_waitcnt lgkmcnt(5)
	v_mfma_f32_32x32x16_bf16 v[48:63], a[0:3], a[8:11], v[48:63]
	v_mfma_f32_32x32x16_bf16 v[32:47], a[4:7], a[8:11], v[32:47]
	s_and_b32 m0, s32, 7
	s_lshl_b32 m0, m0, 11
	s_add_i32 m0, m0, 0x20400
	s_nop 0
	global_load_lds_dwordx4 v[168:169], off
	s_waitcnt lgkmcnt(4)
	v_mfma_f32_32x32x16_bf16 v[16:31], a[0:3], a[12:15], v[16:31]
	v_mfma_f32_32x32x16_bf16 v[0:15], a[4:7], a[12:15], v[0:15]
	s_nop 0
	s_nop 0
	s_nop 0
	s_nop 0
	s_waitcnt lgkmcnt(1)
	v_mfma_f32_32x32x16_bf16 v[48:63], a[16:19], a[24:27], v[48:63]
	v_mfma_f32_32x32x16_bf16 v[32:47], a[20:23], a[24:27], v[32:47]
	s_waitcnt vmcnt(6)
	s_waitcnt lgkmcnt(0)
	s_barrier
	ds_read_b128 a[12:15], v82 offset:53248
	ds_read_b128 a[8:11], v82 offset:49152
	ds_read_b128 a[4:7], v90
	ds_read_b128 a[0:3], v92
	v_mfma_f32_32x32x16_bf16 v[16:31], a[16:19], a[28:31], v[16:31]
	v_lshl_add_u64 v[170:171], v[66:67], 0, s[46:47]
	s_nop 0
	v_lshl_add_u64 v[172:173], v[68:69], 0, s[46:47]
	s_nop 0
	s_nop 0
	s_nop 0
	v_lshl_add_u64 v[174:175], v[70:71], 0, s[46:47]
	s_nop 0
	v_mfma_f32_32x32x16_bf16 v[0:15], a[20:23], a[28:31], v[0:15]
	s_and_b32 m0, s32, 7
	s_lshl_b32 m0, m0, 12
	s_add_i32 m0, m0, 0x0
	s_nop 0
	global_load_lds_dwordx4 v[170:171], off
	s_nop 0
	v_lshl_add_u64 v[176:177], v[72:73], 0, s[46:47]
	s_nop 0
	s_mov_b64 s[38:39], 0x380
	s_nop 0
	v_lshl_add_u64 v[178:179], v[74:75], 0, s[46:47]
	s_nop 0
	v_readfirstlane_b32 s48, v117
	s_nop 0
	v_lshl_add_u64 v[180:181], v[76:77], 0, s[46:47]
	s_nop 0
	s_mov_b64 s[46:47], 0x580
	s_nop 0
	s_nop 0
	s_nop 0
	s_nop 0
	s_nop 0
	ds_read_b128 a[16:19], v93
	ds_read_b128 a[20:23], v91
	ds_read_b128 a[24:27], v84 offset:49152
	ds_read_b128 a[28:31], v84 offset:53248
	s_waitcnt lgkmcnt(4)
	v_mfma_f32_32x32x16_bf16 v[48:63], a[0:3], a[8:11], v[48:63]
	s_nop 0
	v_readfirstlane_b32 s49, v118
	v_readfirstlane_b32 s53, v119
	v_mfma_f32_32x32x16_bf16 v[32:47], a[4:7], a[8:11], v[32:47]
	s_and_b32 m0, s32, 7
	s_lshl_b32 m0, m0, 12
	s_add_i32 m0, m0, 0x400
	s_nop 0
	global_load_lds_dwordx4 v[172:173], off
	v_mfma_f32_32x32x16_bf16 v[16:31], a[0:3], a[12:15], v[16:31]
	v_mfma_f32_32x32x16_bf16 v[0:15], a[4:7], a[12:15], v[0:15]
	s_and_b32 m0, s32, 7
	s_lshl_b32 m0, m0, 12
	s_add_i32 m0, m0, 0x800
	s_nop 0
	global_load_lds_dwordx4 v[174:175], off
	s_nop 0
	s_nop 0
	s_nop 0
	s_nop 0
	ds_read_b128 a[0:3], v95
	ds_read_b128 a[4:7], v94
	ds_read_b128 a[8:11], v86 offset:49152
	ds_read_b128 a[12:15], v86 offset:53248
	s_waitcnt lgkmcnt(5)
	v_mfma_f32_32x32x16_bf16 v[48:63], a[16:19], a[24:27], v[48:63]
	v_mfma_f32_32x32x16_bf16 v[32:47], a[20:23], a[24:27], v[32:47]
	s_and_b32 m0, s32, 7
	s_lshl_b32 m0, m0, 12
	s_add_i32 m0, m0, 0xc00
	s_nop 0
	global_load_lds_dwordx4 v[176:177], off
	s_waitcnt lgkmcnt(4)
	v_mfma_f32_32x32x16_bf16 v[16:31], a[16:19], a[28:31], v[16:31]
	v_mfma_f32_32x32x16_bf16 v[0:15], a[20:23], a[28:31], v[0:15]
	s_and_b32 m0, s32, 7
	s_lshl_b32 m0, m0, 11
	s_add_i32 m0, m0, 0x8000
	s_nop 0
	global_load_lds_dwordx4 v[178:179], off
	s_nop 0
	s_nop 0
	s_nop 0
	s_nop 0
	ds_read_b128 a[16:19], v97
	ds_read_b128 a[20:23], v96
	ds_read_b128 a[24:27], v88 offset:49152
	ds_read_b128 a[28:31], v88 offset:53248
	s_waitcnt lgkmcnt(5)
	v_mfma_f32_32x32x16_bf16 v[48:63], a[0:3], a[8:11], v[48:63]
	v_mfma_f32_32x32x16_bf16 v[32:47], a[4:7], a[8:11], v[32:47]
	s_and_b32 m0, s32, 7
	s_lshl_b32 m0, m0, 11
	s_add_i32 m0, m0, 0x8400
	s_nop 0
	global_load_lds_dwordx4 v[180:181], off
	s_waitcnt lgkmcnt(4)
	v_mfma_f32_32x32x16_bf16 v[16:31], a[0:3], a[12:15], v[16:31]
	v_mfma_f32_32x32x16_bf16 v[0:15], a[4:7], a[12:15], v[0:15]
	s_nop 0
	s_nop 0
	s_nop 0
	s_nop 0
	s_waitcnt lgkmcnt(1)
	v_mfma_f32_32x32x16_bf16 v[48:63], a[16:19], a[24:27], v[48:63]
	v_mfma_f32_32x32x16_bf16 v[32:47], a[20:23], a[24:27], v[32:47]
	s_waitcnt vmcnt(6)
	s_waitcnt lgkmcnt(0)
	s_barrier
	ds_read_b128 a[12:15], v101
	ds_read_b128 a[8:11], v100
	ds_read_b128 a[4:7], v99
	ds_read_b128 a[0:3], v98
	v_mfma_f32_32x32x16_bf16 v[16:31], a[16:19], a[28:31], v[16:31]
	v_lshl_add_u64 v[158:159], v[66:67], 0, s[38:39]
	s_nop 0
	v_lshl_add_u64 v[160:161], v[68:69], 0, s[38:39]
	s_nop 0
	s_mov_b64 s[28:29], 0x400
	s_nop 0
	v_lshl_add_u64 v[162:163], v[70:71], 0, s[38:39]
	s_nop 0
	v_mfma_f32_32x32x16_bf16 v[0:15], a[20:23], a[28:31], v[0:15]
	s_and_b32 m0, s32, 7
	s_lshl_b32 m0, m0, 12
	s_add_i32 m0, m0, 0xc000
	s_nop 0
	global_load_lds_dwordx4 v[158:159], off
	s_nop 0
	v_lshl_add_u64 v[164:165], v[72:73], 0, s[38:39]
	s_nop 0
	v_readfirstlane_b32 s33, v122
	s_nop 0
	v_lshl_add_u64 v[166:167], v[74:75], 0, s[38:39]
	s_nop 0
	v_readfirstlane_b32 s34, v123
	s_nop 0
	v_lshl_add_u64 v[168:169], v[76:77], 0, s[38:39]
	s_nop 0
	s_mov_b64 s[36:37], 0x500
	s_nop 0
	s_nop 0
	s_nop 0
	s_nop 0
	s_nop 0
	ds_read_b128 a[16:19], v102
	ds_read_b128 a[20:23], v103
	ds_read_b128 a[24:27], v104
	ds_read_b128 a[28:31], v105
	s_waitcnt lgkmcnt(4)
	v_mfma_f32_32x32x16_bf16 v[48:63], a[0:3], a[8:11], v[48:63]
	s_nop 0
	v_readfirstlane_b32 s0, v126
	v_readfirstlane_b32 s35, v124
	v_readfirstlane_b32 s38, v115
	v_readfirstlane_b32 s39, v116
	v_mfma_f32_32x32x16_bf16 v[32:47], a[4:7], a[8:11], v[32:47]
	s_and_b32 m0, s32, 7
	s_lshl_b32 m0, m0, 12
	s_add_i32 m0, m0, 0xc400
	s_nop 0
	global_load_lds_dwordx4 v[160:161], off
	v_mfma_f32_32x32x16_bf16 v[16:31], a[0:3], a[12:15], v[16:31]
	v_mfma_f32_32x32x16_bf16 v[0:15], a[4:7], a[12:15], v[0:15]
	s_and_b32 m0, s32, 7
	s_lshl_b32 m0, m0, 12
	s_add_i32 m0, m0, 0xc800
	s_nop 0
	global_load_lds_dwordx4 v[162:163], off
	s_nop 0
	s_nop 0
	s_nop 0
	s_nop 0
	ds_read_b128 a[0:3], v106
	ds_read_b128 a[4:7], v107
	ds_read_b128 a[8:11], v108
	ds_read_b128 a[12:15], v109
	s_waitcnt lgkmcnt(5)
	v_mfma_f32_32x32x16_bf16 v[48:63], a[16:19], a[24:27], v[48:63]
	v_mfma_f32_32x32x16_bf16 v[32:47], a[20:23], a[24:27], v[32:47]
	s_and_b32 m0, s32, 7
	s_lshl_b32 m0, m0, 12
	s_add_i32 m0, m0, 0xcc00
	s_nop 0
	global_load_lds_dwordx4 v[164:165], off
	s_waitcnt lgkmcnt(4)
	v_mfma_f32_32x32x16_bf16 v[16:31], a[16:19], a[28:31], v[16:31]
	v_mfma_f32_32x32x16_bf16 v[0:15], a[20:23], a[28:31], v[0:15]
	s_and_b32 m0, s32, 7
	s_lshl_b32 m0, m0, 11
	s_add_i32 m0, m0, 0x14000
	s_nop 0
	global_load_lds_dwordx4 v[166:167], off
	s_nop 0
	s_nop 0
	s_nop 0
	s_nop 0
	ds_read_b128 a[16:19], v110
	ds_read_b128 a[20:23], v111
	ds_read_b128 a[24:27], v112
	ds_read_b128 a[28:31], v113
	s_waitcnt lgkmcnt(5)
	v_mfma_f32_32x32x16_bf16 v[48:63], a[0:3], a[8:11], v[48:63]
	v_mfma_f32_32x32x16_bf16 v[32:47], a[4:7], a[8:11], v[32:47]
	s_and_b32 m0, s32, 7
	s_lshl_b32 m0, m0, 11
	s_add_i32 m0, m0, 0x14400
	s_nop 0
	global_load_lds_dwordx4 v[168:169], off
	s_waitcnt lgkmcnt(4)
	v_mfma_f32_32x32x16_bf16 v[16:31], a[0:3], a[12:15], v[16:31]
	v_mfma_f32_32x32x16_bf16 v[0:15], a[4:7], a[12:15], v[0:15]
	s_nop 0
	s_nop 0
	s_nop 0
	s_nop 0
	s_waitcnt lgkmcnt(1)
	v_mfma_f32_32x32x16_bf16 v[48:63], a[16:19], a[24:27], v[48:63]
	v_mfma_f32_32x32x16_bf16 v[32:47], a[20:23], a[24:27], v[32:47]
	s_waitcnt vmcnt(6)
	s_waitcnt lgkmcnt(0)
	s_barrier
	ds_read_b128 a[12:15], v82 offset:4096
	ds_read_b128 a[8:11], v82
	ds_read_b128 a[4:7], v83 offset:36864
	ds_read_b128 a[0:3], v83 offset:32768
	v_mfma_f32_32x32x16_bf16 v[16:31], a[16:19], a[28:31], v[16:31]
	v_lshl_add_u64 v[170:171], v[66:67], 0, s[28:29]
	s_nop 0
	v_lshl_add_u64 v[172:173], v[68:69], 0, s[28:29]
	s_nop 0
	v_readfirstlane_b32 s1, v127
	s_nop 0
	v_lshl_add_u64 v[174:175], v[70:71], 0, s[28:29]
	s_nop 0
	v_mfma_f32_32x32x16_bf16 v[0:15], a[20:23], a[28:31], v[0:15]
	s_and_b32 m0, s32, 7
	s_lshl_b32 m0, m0, 12
	s_add_i32 m0, m0, 0x18000
	s_nop 0
	global_load_lds_dwordx4 v[170:171], off
	s_nop 0
	v_lshl_add_u64 v[176:177], v[72:73], 0, s[28:29]
	s_nop 0
	v_readfirstlane_b32 s20, v128
	s_nop 0
	v_lshl_add_u64 v[178:179], v[74:75], 0, s[28:29]
	s_nop 0
	v_readfirstlane_b32 s21, v129
	s_nop 0
	v_lshl_add_u64 v[180:181], v[76:77], 0, s[28:29]
	s_nop 0
	s_mov_b64 s[28:29], 0x480
	s_nop 0
	s_nop 0
	s_nop 0
	s_nop 0
	s_nop 0
	ds_read_b128 a[16:19], v85 offset:32768
	ds_read_b128 a[20:23], v85 offset:36864
	ds_read_b128 a[24:27], v84
	ds_read_b128 a[28:31], v84 offset:4096
	s_waitcnt lgkmcnt(4)
	v_mfma_f32_32x32x16_bf16 v[48:63], a[0:3], a[8:11], v[48:63]
	s_nop 0
	v_lshl_add_u64 v[162:163], v[70:71], 0, s[28:29]
	v_readfirstlane_b32 s23, v131
	v_readfirstlane_b32 s24, v130
	v_mfma_f32_32x32x16_bf16 v[32:47], a[4:7], a[8:11], v[32:47]
	s_and_b32 m0, s32, 7
	s_lshl_b32 m0, m0, 12
	s_add_i32 m0, m0, 0x18400
	s_nop 0
	global_load_lds_dwordx4 v[172:173], off
	v_mfma_f32_32x32x16_bf16 v[16:31], a[0:3], a[12:15], v[16:31]
	v_mfma_f32_32x32x16_bf16 v[0:15], a[4:7], a[12:15], v[0:15]
	s_and_b32 m0, s32, 7
	s_lshl_b32 m0, m0, 12
	s_add_i32 m0, m0, 0x18800
	s_nop 0
	global_load_lds_dwordx4 v[174:175], off
	s_nop 0
	s_nop 0
	s_nop 0
	s_nop 0
	ds_read_b128 a[0:3], v87 offset:32768
	ds_read_b128 a[4:7], v87 offset:36864
	ds_read_b128 a[8:11], v86
	ds_read_b128 a[12:15], v86 offset:4096
	s_waitcnt lgkmcnt(5)
	v_mfma_f32_32x32x16_bf16 v[48:63], a[16:19], a[24:27], v[48:63]
	v_mfma_f32_32x32x16_bf16 v[32:47], a[20:23], a[24:27], v[32:47]
	s_and_b32 m0, s32, 7
	s_lshl_b32 m0, m0, 12
	s_add_i32 m0, m0, 0x18c00
	s_nop 0
	global_load_lds_dwordx4 v[176:177], off
	s_waitcnt lgkmcnt(4)
	v_mfma_f32_32x32x16_bf16 v[16:31], a[16:19], a[28:31], v[16:31]
	v_mfma_f32_32x32x16_bf16 v[0:15], a[20:23], a[28:31], v[0:15]
	s_and_b32 m0, s32, 7
	s_lshl_b32 m0, m0, 11
	s_add_i32 m0, m0, 0x20000
	s_nop 0
	global_load_lds_dwordx4 v[178:179], off
	s_nop 0
	s_nop 0
	s_nop 0
	s_nop 0
	ds_read_b128 a[16:19], v89 offset:32768
	ds_read_b128 a[20:23], v89 offset:36864
	ds_read_b128 a[24:27], v88
	ds_read_b128 a[28:31], v88 offset:4096
	s_waitcnt lgkmcnt(5)
	v_mfma_f32_32x32x16_bf16 v[48:63], a[0:3], a[8:11], v[48:63]
	v_mfma_f32_32x32x16_bf16 v[32:47], a[4:7], a[8:11], v[32:47]
	s_and_b32 m0, s32, 7
	s_lshl_b32 m0, m0, 11
	s_add_i32 m0, m0, 0x20400
	s_nop 0
	global_load_lds_dwordx4 v[180:181], off
	s_waitcnt lgkmcnt(4)
	v_mfma_f32_32x32x16_bf16 v[16:31], a[0:3], a[12:15], v[16:31]
	v_mfma_f32_32x32x16_bf16 v[0:15], a[4:7], a[12:15], v[0:15]
	s_nop 0
	s_nop 0
	s_nop 0
	s_nop 0
	s_waitcnt lgkmcnt(1)
	v_mfma_f32_32x32x16_bf16 v[48:63], a[16:19], a[24:27], v[48:63]
	v_mfma_f32_32x32x16_bf16 v[32:47], a[20:23], a[24:27], v[32:47]
	s_waitcnt vmcnt(6)
	s_waitcnt lgkmcnt(0)
	s_barrier
	ds_read_b128 a[12:15], v82 offset:53248
	ds_read_b128 a[8:11], v82 offset:49152
	ds_read_b128 a[4:7], v90
	ds_read_b128 a[0:3], v92
	v_mfma_f32_32x32x16_bf16 v[16:31], a[16:19], a[28:31], v[16:31]
	v_lshl_add_u64 v[158:159], v[66:67], 0, s[28:29]
	s_nop 0
	v_lshl_add_u64 v[160:161], v[68:69], 0, s[28:29]
	s_nop 0
	s_nop 0
	s_nop 0
	s_nop 0
	v_mfma_f32_32x32x16_bf16 v[0:15], a[20:23], a[28:31], v[0:15]
	s_and_b32 m0, s32, 7
	s_lshl_b32 m0, m0, 12
	s_add_i32 m0, m0, 0x0
	s_nop 0
	global_load_lds_dwordx4 v[158:159], off
	s_nop 0
	v_lshl_add_u64 v[164:165], v[72:73], 0, s[28:29]
	s_nop 0
	s_nop 0
	s_nop 0
	v_lshl_add_u64 v[166:167], v[74:75], 0, s[28:29]
	s_nop 0
	s_nop 0
	s_nop 0
	v_lshl_add_u64 v[168:169], v[76:77], 0, s[28:29]
	s_nop 0
	v_readfirstlane_b32 s28, v120
	s_nop 0
	s_nop 0
	s_nop 0
	s_nop 0
	s_nop 0
	ds_read_b128 a[16:19], v93
	ds_read_b128 a[20:23], v91
	ds_read_b128 a[24:27], v84 offset:49152
	ds_read_b128 a[28:31], v84 offset:53248
	s_waitcnt lgkmcnt(4)
	v_mfma_f32_32x32x16_bf16 v[48:63], a[0:3], a[8:11], v[48:63]
	s_nop 0
	v_readfirstlane_b32 s29, v121
	v_lshl_add_u64 v[174:175], v[70:71], 0, s[36:37]
	v_mfma_f32_32x32x16_bf16 v[32:47], a[4:7], a[8:11], v[32:47]
	s_and_b32 m0, s32, 7
	s_lshl_b32 m0, m0, 12
	s_add_i32 m0, m0, 0x400
	s_nop 0
	global_load_lds_dwordx4 v[160:161], off
	v_mfma_f32_32x32x16_bf16 v[16:31], a[0:3], a[12:15], v[16:31]
	v_mfma_f32_32x32x16_bf16 v[0:15], a[4:7], a[12:15], v[0:15]
	s_and_b32 m0, s32, 7
	s_lshl_b32 m0, m0, 12
	s_add_i32 m0, m0, 0x800
	s_nop 0
	global_load_lds_dwordx4 v[162:163], off
	s_nop 0
	s_nop 0
	s_nop 0
	s_nop 0
	ds_read_b128 a[0:3], v95
	ds_read_b128 a[4:7], v94
	ds_read_b128 a[8:11], v86 offset:49152
	ds_read_b128 a[12:15], v86 offset:53248
	s_waitcnt lgkmcnt(5)
	v_mfma_f32_32x32x16_bf16 v[48:63], a[16:19], a[24:27], v[48:63]
	v_mfma_f32_32x32x16_bf16 v[32:47], a[20:23], a[24:27], v[32:47]
	s_and_b32 m0, s32, 7
	s_lshl_b32 m0, m0, 12
	s_add_i32 m0, m0, 0xc00
	s_nop 0
	global_load_lds_dwordx4 v[164:165], off
	s_waitcnt lgkmcnt(4)
	v_mfma_f32_32x32x16_bf16 v[16:31], a[16:19], a[28:31], v[16:31]
	v_mfma_f32_32x32x16_bf16 v[0:15], a[20:23], a[28:31], v[0:15]
	s_and_b32 m0, s32, 7
	s_lshl_b32 m0, m0, 11
	s_add_i32 m0, m0, 0x8000
	s_nop 0
	global_load_lds_dwordx4 v[166:167], off
	s_nop 0
	s_nop 0
	s_nop 0
	s_nop 0
	ds_read_b128 a[16:19], v97
	ds_read_b128 a[20:23], v96
	ds_read_b128 a[24:27], v88 offset:49152
	ds_read_b128 a[28:31], v88 offset:53248
	s_waitcnt lgkmcnt(5)
	v_mfma_f32_32x32x16_bf16 v[48:63], a[0:3], a[8:11], v[48:63]
	v_mfma_f32_32x32x16_bf16 v[32:47], a[4:7], a[8:11], v[32:47]
	s_and_b32 m0, s32, 7
	s_lshl_b32 m0, m0, 11
	s_add_i32 m0, m0, 0x8400
	s_nop 0
	global_load_lds_dwordx4 v[168:169], off
	s_waitcnt lgkmcnt(4)
	v_mfma_f32_32x32x16_bf16 v[16:31], a[0:3], a[12:15], v[16:31]
	v_mfma_f32_32x32x16_bf16 v[0:15], a[4:7], a[12:15], v[0:15]
	s_nop 0
	s_nop 0
	s_nop 0
	s_nop 0
	s_waitcnt lgkmcnt(1)
	v_mfma_f32_32x32x16_bf16 v[48:63], a[16:19], a[24:27], v[48:63]
	v_mfma_f32_32x32x16_bf16 v[32:47], a[20:23], a[24:27], v[32:47]
	s_waitcnt vmcnt(6)
	s_waitcnt lgkmcnt(0)
	s_barrier
	ds_read_b128 a[12:15], v101
	ds_read_b128 a[8:11], v100
	ds_read_b128 a[4:7], v99
	ds_read_b128 a[0:3], v98
	v_mfma_f32_32x32x16_bf16 v[16:31], a[16:19], a[28:31], v[16:31]
	v_lshl_add_u64 v[170:171], v[66:67], 0, s[36:37]
	s_nop 0
	v_lshl_add_u64 v[172:173], v[68:69], 0, s[36:37]
	s_nop 0
	s_nop 0
	s_nop 0
	s_nop 0
	v_mfma_f32_32x32x16_bf16 v[0:15], a[20:23], a[28:31], v[0:15]
	s_and_b32 m0, s32, 7
	s_lshl_b32 m0, m0, 12
	s_add_i32 m0, m0, 0xc000
	s_nop 0
	global_load_lds_dwordx4 v[170:171], off
	s_nop 0
	v_lshl_add_u64 v[176:177], v[72:73], 0, s[36:37]
	s_nop 0
	s_nop 0
	s_nop 0
	v_lshl_add_u64 v[178:179], v[74:75], 0, s[36:37]
	s_nop 0
	s_nop 0
	s_nop 0
	v_lshl_add_u64 v[180:181], v[76:77], 0, s[36:37]
	v_readfirstlane_b32 s36, v125
	s_nop 0
	v_readfirstlane_b32 s37, v114
	s_nop 0
	s_nop 0
	s_nop 0
	s_nop 0
	s_nop 0
	ds_read_b128 a[16:19], v102
	ds_read_b128 a[20:23], v103
	ds_read_b128 a[24:27], v104
	ds_read_b128 a[28:31], v105
	s_waitcnt lgkmcnt(4)
	v_mfma_f32_32x32x16_bf16 v[48:63], a[0:3], a[8:11], v[48:63]
	s_nop 0
	v_lshl_add_u64 v[162:163], v[70:71], 0, s[46:47]
	v_mfma_f32_32x32x16_bf16 v[32:47], a[4:7], a[8:11], v[32:47]
	s_and_b32 m0, s32, 7
	s_lshl_b32 m0, m0, 12
	s_add_i32 m0, m0, 0xc400
	s_nop 0
	global_load_lds_dwordx4 v[172:173], off
	v_mfma_f32_32x32x16_bf16 v[16:31], a[0:3], a[12:15], v[16:31]
	v_mfma_f32_32x32x16_bf16 v[0:15], a[4:7], a[12:15], v[0:15]
	s_and_b32 m0, s32, 7
	s_lshl_b32 m0, m0, 12
	s_add_i32 m0, m0, 0xc800
	s_nop 0
	global_load_lds_dwordx4 v[174:175], off
	s_nop 0
	s_nop 0
	s_nop 0
	s_nop 0
	ds_read_b128 a[0:3], v106
	ds_read_b128 a[4:7], v107
	ds_read_b128 a[8:11], v108
	ds_read_b128 a[12:15], v109
	s_waitcnt lgkmcnt(5)
	v_mfma_f32_32x32x16_bf16 v[48:63], a[16:19], a[24:27], v[48:63]
	v_mfma_f32_32x32x16_bf16 v[32:47], a[20:23], a[24:27], v[32:47]
	s_and_b32 m0, s32, 7
	s_lshl_b32 m0, m0, 12
	s_add_i32 m0, m0, 0xcc00
	s_nop 0
	global_load_lds_dwordx4 v[176:177], off
	s_waitcnt lgkmcnt(4)
	v_mfma_f32_32x32x16_bf16 v[16:31], a[16:19], a[28:31], v[16:31]
	v_mfma_f32_32x32x16_bf16 v[0:15], a[20:23], a[28:31], v[0:15]
	s_and_b32 m0, s32, 7
	s_lshl_b32 m0, m0, 11
	s_add_i32 m0, m0, 0x14000
	s_nop 0
	global_load_lds_dwordx4 v[178:179], off
	s_nop 0
	s_nop 0
	s_nop 0
	s_nop 0
	ds_read_b128 a[16:19], v110
	ds_read_b128 a[20:23], v111
	ds_read_b128 a[24:27], v112
	ds_read_b128 a[28:31], v113
	s_waitcnt lgkmcnt(5)
	v_mfma_f32_32x32x16_bf16 v[48:63], a[0:3], a[8:11], v[48:63]
	v_mfma_f32_32x32x16_bf16 v[32:47], a[4:7], a[8:11], v[32:47]
	s_and_b32 m0, s32, 7
	s_lshl_b32 m0, m0, 11
	s_add_i32 m0, m0, 0x14400
	s_nop 0
	global_load_lds_dwordx4 v[180:181], off
	s_waitcnt lgkmcnt(4)
	v_mfma_f32_32x32x16_bf16 v[16:31], a[0:3], a[12:15], v[16:31]
	v_mfma_f32_32x32x16_bf16 v[0:15], a[4:7], a[12:15], v[0:15]
	s_nop 0
	s_nop 0
	s_nop 0
	s_nop 0
	s_waitcnt lgkmcnt(1)
	v_mfma_f32_32x32x16_bf16 v[48:63], a[16:19], a[24:27], v[48:63]
	v_mfma_f32_32x32x16_bf16 v[32:47], a[20:23], a[24:27], v[32:47]
	s_waitcnt vmcnt(6)
	s_waitcnt lgkmcnt(0)
	s_barrier
	ds_read_b128 a[12:15], v82 offset:4096
	ds_read_b128 a[8:11], v82
	ds_read_b128 a[4:7], v83 offset:36864
	ds_read_b128 a[0:3], v83 offset:32768
	v_mfma_f32_32x32x16_bf16 v[16:31], a[16:19], a[28:31], v[16:31]
	v_lshl_add_u64 v[158:159], v[66:67], 0, s[46:47]
	s_nop 0
	v_lshl_add_u64 v[160:161], v[68:69], 0, s[46:47]
	s_nop 0
	s_nop 0
	s_nop 0
	s_nop 0
	v_mfma_f32_32x32x16_bf16 v[0:15], a[20:23], a[28:31], v[0:15]
	s_and_b32 m0, s32, 7
	s_lshl_b32 m0, m0, 12
	s_add_i32 m0, m0, 0x18000
	s_nop 0
	global_load_lds_dwordx4 v[158:159], off
	s_nop 0
	v_lshl_add_u64 v[164:165], v[72:73], 0, s[46:47]
	s_nop 0
	s_nop 0
	s_nop 0
	v_lshl_add_u64 v[166:167], v[74:75], 0, s[46:47]
	s_nop 0
	s_nop 0
	s_nop 0
	v_lshl_add_u64 v[168:169], v[76:77], 0, s[46:47]
	s_nop 0
	s_mov_b64 s[46:47], 0x600
	s_nop 0
	s_nop 0
	s_nop 0
	s_nop 0
	s_nop 0
	ds_read_b128 a[16:19], v85 offset:32768
	ds_read_b128 a[20:23], v85 offset:36864
	ds_read_b128 a[24:27], v84
	ds_read_b128 a[28:31], v84 offset:4096
	s_waitcnt lgkmcnt(4)
	v_mfma_f32_32x32x16_bf16 v[48:63], a[0:3], a[8:11], v[48:63]
	s_nop 0
	v_mfma_f32_32x32x16_bf16 v[32:47], a[4:7], a[8:11], v[32:47]
	s_and_b32 m0, s32, 7
	s_lshl_b32 m0, m0, 12
	s_add_i32 m0, m0, 0x18400
	s_nop 0
	global_load_lds_dwordx4 v[160:161], off
	v_mfma_f32_32x32x16_bf16 v[16:31], a[0:3], a[12:15], v[16:31]
	v_mfma_f32_32x32x16_bf16 v[0:15], a[4:7], a[12:15], v[0:15]
	s_and_b32 m0, s32, 7
	s_lshl_b32 m0, m0, 12
	s_add_i32 m0, m0, 0x18800
	s_nop 0
	global_load_lds_dwordx4 v[162:163], off
	s_nop 0
	s_nop 0
	s_nop 0
	s_nop 0
	ds_read_b128 a[0:3], v87 offset:32768
	ds_read_b128 a[4:7], v87 offset:36864
	ds_read_b128 a[8:11], v86
	ds_read_b128 a[12:15], v86 offset:4096
	s_waitcnt lgkmcnt(5)
	v_mfma_f32_32x32x16_bf16 v[48:63], a[16:19], a[24:27], v[48:63]
	v_mfma_f32_32x32x16_bf16 v[32:47], a[20:23], a[24:27], v[32:47]
	s_and_b32 m0, s32, 7
	s_lshl_b32 m0, m0, 12
	s_add_i32 m0, m0, 0x18c00
	s_nop 0
	global_load_lds_dwordx4 v[164:165], off
	s_waitcnt lgkmcnt(4)
	v_mfma_f32_32x32x16_bf16 v[16:31], a[16:19], a[28:31], v[16:31]
	v_mfma_f32_32x32x16_bf16 v[0:15], a[20:23], a[28:31], v[0:15]
	s_and_b32 m0, s32, 7
	s_lshl_b32 m0, m0, 11
	s_add_i32 m0, m0, 0x20000
	s_nop 0
	global_load_lds_dwordx4 v[166:167], off
	s_nop 0
	s_nop 0
	s_nop 0
	s_nop 0
	ds_read_b128 a[16:19], v89 offset:32768
	ds_read_b128 a[20:23], v89 offset:36864
	ds_read_b128 a[24:27], v88
	ds_read_b128 a[28:31], v88 offset:4096
	s_waitcnt lgkmcnt(5)
	v_mfma_f32_32x32x16_bf16 v[48:63], a[0:3], a[8:11], v[48:63]
	v_mfma_f32_32x32x16_bf16 v[32:47], a[4:7], a[8:11], v[32:47]
	s_and_b32 m0, s32, 7
	s_lshl_b32 m0, m0, 11
	s_add_i32 m0, m0, 0x20400
	s_nop 0
	global_load_lds_dwordx4 v[168:169], off
	s_waitcnt lgkmcnt(4)
	v_mfma_f32_32x32x16_bf16 v[16:31], a[0:3], a[12:15], v[16:31]
	v_mfma_f32_32x32x16_bf16 v[0:15], a[4:7], a[12:15], v[0:15]
	s_nop 0
	s_nop 0
	s_nop 0
	s_nop 0
	s_waitcnt lgkmcnt(1)
	v_mfma_f32_32x32x16_bf16 v[48:63], a[16:19], a[24:27], v[48:63]
	v_mfma_f32_32x32x16_bf16 v[32:47], a[20:23], a[24:27], v[32:47]
	s_waitcnt vmcnt(6)
	s_waitcnt lgkmcnt(0)
	s_barrier
	ds_read_b128 a[12:15], v82 offset:53248
	ds_read_b128 a[8:11], v82 offset:49152
	ds_read_b128 a[4:7], v90
	ds_read_b128 a[0:3], v92
	v_mfma_f32_32x32x16_bf16 v[16:31], a[16:19], a[28:31], v[16:31]
	v_lshl_add_u64 v[170:171], v[66:67], 0, s[46:47]
	s_nop 0
	v_lshl_add_u64 v[172:173], v[68:69], 0, s[46:47]
	s_nop 0
	s_nop 0
	s_nop 0
	v_lshl_add_u64 v[174:175], v[70:71], 0, s[46:47]
	s_nop 0
	v_mfma_f32_32x32x16_bf16 v[0:15], a[20:23], a[28:31], v[0:15]
	s_and_b32 m0, s32, 7
	s_lshl_b32 m0, m0, 12
	s_add_i32 m0, m0, 0x0
	s_nop 0
	global_load_lds_dwordx4 v[170:171], off
	s_nop 0
	v_lshl_add_u64 v[176:177], v[72:73], 0, s[46:47]
	s_nop 0
	s_nop 0
	s_nop 0
	v_lshl_add_u64 v[178:179], v[74:75], 0, s[46:47]
	s_nop 0
	s_nop 0
	s_nop 0
	v_lshl_add_u64 v[180:181], v[76:77], 0, s[46:47]
	s_nop 0
	s_mov_b64 s[46:47], 0x680
	s_nop 0
	s_nop 0
	s_nop 0
	s_nop 0
	s_nop 0
	ds_read_b128 a[16:19], v93
	ds_read_b128 a[20:23], v91
	ds_read_b128 a[24:27], v84 offset:49152
	ds_read_b128 a[28:31], v84 offset:53248
	s_waitcnt lgkmcnt(4)
	v_mfma_f32_32x32x16_bf16 v[48:63], a[0:3], a[8:11], v[48:63]
	s_nop 0
	v_mfma_f32_32x32x16_bf16 v[32:47], a[4:7], a[8:11], v[32:47]
	s_and_b32 m0, s32, 7
	s_lshl_b32 m0, m0, 12
	s_add_i32 m0, m0, 0x400
	s_nop 0
	global_load_lds_dwordx4 v[172:173], off
	v_mfma_f32_32x32x16_bf16 v[16:31], a[0:3], a[12:15], v[16:31]
	v_mfma_f32_32x32x16_bf16 v[0:15], a[4:7], a[12:15], v[0:15]
	s_and_b32 m0, s32, 7
	s_lshl_b32 m0, m0, 12
	s_add_i32 m0, m0, 0x800
	s_nop 0
	global_load_lds_dwordx4 v[174:175], off
	s_nop 0
	s_nop 0
	s_nop 0
	s_nop 0
	ds_read_b128 a[0:3], v95
	ds_read_b128 a[4:7], v94
	ds_read_b128 a[8:11], v86 offset:49152
	ds_read_b128 a[12:15], v86 offset:53248
	s_waitcnt lgkmcnt(5)
	v_mfma_f32_32x32x16_bf16 v[48:63], a[16:19], a[24:27], v[48:63]
	v_mfma_f32_32x32x16_bf16 v[32:47], a[20:23], a[24:27], v[32:47]
	s_and_b32 m0, s32, 7
	s_lshl_b32 m0, m0, 12
	s_add_i32 m0, m0, 0xc00
	s_nop 0
	global_load_lds_dwordx4 v[176:177], off
	s_waitcnt lgkmcnt(4)
	v_mfma_f32_32x32x16_bf16 v[16:31], a[16:19], a[28:31], v[16:31]
	v_mfma_f32_32x32x16_bf16 v[0:15], a[20:23], a[28:31], v[0:15]
	s_and_b32 m0, s32, 7
	s_lshl_b32 m0, m0, 11
	s_add_i32 m0, m0, 0x8000
	s_nop 0
	global_load_lds_dwordx4 v[178:179], off
	s_nop 0
	s_nop 0
	s_nop 0
	s_nop 0
	ds_read_b128 a[16:19], v97
	ds_read_b128 a[20:23], v96
	ds_read_b128 a[24:27], v88 offset:49152
	ds_read_b128 a[28:31], v88 offset:53248
	s_waitcnt lgkmcnt(5)
	v_mfma_f32_32x32x16_bf16 v[48:63], a[0:3], a[8:11], v[48:63]
	v_mfma_f32_32x32x16_bf16 v[32:47], a[4:7], a[8:11], v[32:47]
	s_and_b32 m0, s32, 7
	s_lshl_b32 m0, m0, 11
	s_add_i32 m0, m0, 0x8400
	s_nop 0
	global_load_lds_dwordx4 v[180:181], off
	s_waitcnt lgkmcnt(4)
	v_mfma_f32_32x32x16_bf16 v[16:31], a[0:3], a[12:15], v[16:31]
	v_mfma_f32_32x32x16_bf16 v[0:15], a[4:7], a[12:15], v[0:15]
	s_nop 0
	s_nop 0
	s_nop 0
	s_nop 0
	s_waitcnt lgkmcnt(1)
	v_mfma_f32_32x32x16_bf16 v[48:63], a[16:19], a[24:27], v[48:63]
	v_mfma_f32_32x32x16_bf16 v[32:47], a[20:23], a[24:27], v[32:47]
	s_waitcnt vmcnt(6)
	s_waitcnt lgkmcnt(0)
	s_barrier
	ds_read_b128 a[12:15], v101
	ds_read_b128 a[8:11], v100
	ds_read_b128 a[4:7], v99
	ds_read_b128 a[0:3], v98
	v_mfma_f32_32x32x16_bf16 v[16:31], a[16:19], a[28:31], v[16:31]
	v_lshl_add_u64 v[158:159], v[66:67], 0, s[46:47]
	s_nop 0
	v_lshl_add_u64 v[160:161], v[68:69], 0, s[46:47]
	s_nop 0
	s_mov_b64 s[28:29], 0x700
	s_nop 0
	v_lshl_add_u64 v[162:163], v[70:71], 0, s[46:47]
	s_nop 0
	v_mfma_f32_32x32x16_bf16 v[0:15], a[20:23], a[28:31], v[0:15]
	s_and_b32 m0, s32, 7
	s_lshl_b32 m0, m0, 12
	s_add_i32 m0, m0, 0xc000
	s_nop 0
	global_load_lds_dwordx4 v[158:159], off
	s_nop 0
	v_lshl_add_u64 v[164:165], v[72:73], 0, s[46:47]
	s_nop 0
	s_nop 0
	s_nop 0
	v_lshl_add_u64 v[166:167], v[74:75], 0, s[46:47]
	s_nop 0
	s_nop 0
	s_nop 0
	v_lshl_add_u64 v[168:169], v[76:77], 0, s[46:47]
	s_nop 0
	s_nop 0
	s_nop 0
	s_nop 0
	s_nop 0
	s_nop 0
	s_nop 0
	ds_read_b128 a[16:19], v102
	ds_read_b128 a[20:23], v103
	ds_read_b128 a[24:27], v104
	ds_read_b128 a[28:31], v105
	s_waitcnt lgkmcnt(4)
	v_mfma_f32_32x32x16_bf16 v[48:63], a[0:3], a[8:11], v[48:63]
	s_nop 0
	v_mfma_f32_32x32x16_bf16 v[32:47], a[4:7], a[8:11], v[32:47]
	s_and_b32 m0, s32, 7
	s_lshl_b32 m0, m0, 12
	s_add_i32 m0, m0, 0xc400
	s_nop 0
	global_load_lds_dwordx4 v[160:161], off
	v_mfma_f32_32x32x16_bf16 v[16:31], a[0:3], a[12:15], v[16:31]
	v_mfma_f32_32x32x16_bf16 v[0:15], a[4:7], a[12:15], v[0:15]
	s_and_b32 m0, s32, 7
	s_lshl_b32 m0, m0, 12
	s_add_i32 m0, m0, 0xc800
	s_nop 0
	global_load_lds_dwordx4 v[162:163], off
	s_nop 0
	s_nop 0
	s_nop 0
	s_nop 0
	ds_read_b128 a[0:3], v106
	ds_read_b128 a[4:7], v107
	ds_read_b128 a[8:11], v108
	ds_read_b128 a[12:15], v109
	s_waitcnt lgkmcnt(5)
	v_mfma_f32_32x32x16_bf16 v[48:63], a[16:19], a[24:27], v[48:63]
	v_mfma_f32_32x32x16_bf16 v[32:47], a[20:23], a[24:27], v[32:47]
	s_and_b32 m0, s32, 7
	s_lshl_b32 m0, m0, 12
	s_add_i32 m0, m0, 0xcc00
	s_nop 0
	global_load_lds_dwordx4 v[164:165], off
	s_waitcnt lgkmcnt(4)
	v_mfma_f32_32x32x16_bf16 v[16:31], a[16:19], a[28:31], v[16:31]
	v_mfma_f32_32x32x16_bf16 v[0:15], a[20:23], a[28:31], v[0:15]
	s_and_b32 m0, s32, 7
	s_lshl_b32 m0, m0, 11
	s_add_i32 m0, m0, 0x14000
	s_nop 0
	global_load_lds_dwordx4 v[166:167], off
	s_nop 0
	s_nop 0
	s_nop 0
	s_nop 0
	ds_read_b128 a[16:19], v110
	ds_read_b128 a[20:23], v111
	ds_read_b128 a[24:27], v112
	ds_read_b128 a[28:31], v113
	s_waitcnt lgkmcnt(5)
	v_mfma_f32_32x32x16_bf16 v[48:63], a[0:3], a[8:11], v[48:63]
	v_mfma_f32_32x32x16_bf16 v[32:47], a[4:7], a[8:11], v[32:47]
	s_and_b32 m0, s32, 7
	s_lshl_b32 m0, m0, 11
	s_add_i32 m0, m0, 0x14400
	s_nop 0
	global_load_lds_dwordx4 v[168:169], off
	s_waitcnt lgkmcnt(4)
	v_mfma_f32_32x32x16_bf16 v[16:31], a[0:3], a[12:15], v[16:31]
	v_mfma_f32_32x32x16_bf16 v[0:15], a[4:7], a[12:15], v[0:15]
	s_nop 0
	s_nop 0
	s_nop 0
	s_nop 0
	s_waitcnt lgkmcnt(1)
	v_mfma_f32_32x32x16_bf16 v[48:63], a[16:19], a[24:27], v[48:63]
	v_mfma_f32_32x32x16_bf16 v[32:47], a[20:23], a[24:27], v[32:47]
	s_waitcnt vmcnt(6)
	s_waitcnt lgkmcnt(0)
	s_barrier
	ds_read_b128 a[12:15], v82 offset:4096
	ds_read_b128 a[8:11], v82
	ds_read_b128 a[4:7], v83 offset:36864
	ds_read_b128 a[0:3], v83 offset:32768
	v_mfma_f32_32x32x16_bf16 v[16:31], a[16:19], a[28:31], v[16:31]
	v_lshl_add_u64 v[170:171], v[66:67], 0, s[28:29]
	s_nop 0
	v_lshl_add_u64 v[172:173], v[68:69], 0, s[28:29]
	s_nop 0
	s_nop 0
	s_nop 0
	v_lshl_add_u64 v[174:175], v[70:71], 0, s[28:29]
	s_nop 0
	v_mfma_f32_32x32x16_bf16 v[0:15], a[20:23], a[28:31], v[0:15]
	s_and_b32 m0, s32, 7
	s_lshl_b32 m0, m0, 12
	s_add_i32 m0, m0, 0x18000
	s_nop 0
	global_load_lds_dwordx4 v[170:171], off
	s_nop 0
	v_lshl_add_u64 v[176:177], v[72:73], 0, s[28:29]
	s_nop 0
	s_nop 0
	s_nop 0
	v_lshl_add_u64 v[178:179], v[74:75], 0, s[28:29]
	s_nop 0
	s_nop 0
	s_nop 0
	v_lshl_add_u64 v[180:181], v[76:77], 0, s[28:29]
	s_nop 0
	s_mov_b64 s[28:29], 0x780
	s_nop 0
	s_nop 0
	s_nop 0
	s_nop 0
	s_nop 0
	ds_read_b128 a[16:19], v85 offset:32768
	ds_read_b128 a[20:23], v85 offset:36864
	ds_read_b128 a[24:27], v84
	ds_read_b128 a[28:31], v84 offset:4096
	s_waitcnt lgkmcnt(4)
	v_mfma_f32_32x32x16_bf16 v[48:63], a[0:3], a[8:11], v[48:63]
	v_lshl_add_u64 v[158:159], v[66:67], 0, s[28:29]
	s_nop 0
	v_mfma_f32_32x32x16_bf16 v[32:47], a[4:7], a[8:11], v[32:47]
	s_and_b32 m0, s32, 7
	s_lshl_b32 m0, m0, 12
	s_add_i32 m0, m0, 0x18400
	s_nop 0
	global_load_lds_dwordx4 v[172:173], off
	v_mfma_f32_32x32x16_bf16 v[16:31], a[0:3], a[12:15], v[16:31]
	v_mfma_f32_32x32x16_bf16 v[0:15], a[4:7], a[12:15], v[0:15]
	s_and_b32 m0, s32, 7
	s_lshl_b32 m0, m0, 12
	s_add_i32 m0, m0, 0x18800
	s_nop 0
	global_load_lds_dwordx4 v[174:175], off
	s_nop 0
	s_nop 0
	s_nop 0
	s_nop 0
	ds_read_b128 a[0:3], v87 offset:32768
	ds_read_b128 a[4:7], v87 offset:36864
	ds_read_b128 a[8:11], v86
	ds_read_b128 a[12:15], v86 offset:4096
	s_waitcnt lgkmcnt(5)
	v_mfma_f32_32x32x16_bf16 v[48:63], a[16:19], a[24:27], v[48:63]
	v_mfma_f32_32x32x16_bf16 v[32:47], a[20:23], a[24:27], v[32:47]
	s_and_b32 m0, s32, 7
	s_lshl_b32 m0, m0, 12
	s_add_i32 m0, m0, 0x18c00
	s_nop 0
	global_load_lds_dwordx4 v[176:177], off
	s_waitcnt lgkmcnt(4)
	v_mfma_f32_32x32x16_bf16 v[16:31], a[16:19], a[28:31], v[16:31]
	v_mfma_f32_32x32x16_bf16 v[0:15], a[20:23], a[28:31], v[0:15]
	s_and_b32 m0, s32, 7
	s_lshl_b32 m0, m0, 11
	s_add_i32 m0, m0, 0x20000
	s_nop 0
	global_load_lds_dwordx4 v[178:179], off
	s_nop 0
	s_nop 0
	s_nop 0
	s_nop 0
	ds_read_b128 a[16:19], v89 offset:32768
	ds_read_b128 a[20:23], v89 offset:36864
	ds_read_b128 a[24:27], v88
	ds_read_b128 a[28:31], v88 offset:4096
	s_waitcnt lgkmcnt(5)
	v_mfma_f32_32x32x16_bf16 v[48:63], a[0:3], a[8:11], v[48:63]
	v_mfma_f32_32x32x16_bf16 v[32:47], a[4:7], a[8:11], v[32:47]
	s_and_b32 m0, s32, 7
	s_lshl_b32 m0, m0, 11
	s_add_i32 m0, m0, 0x20400
	s_nop 0
	global_load_lds_dwordx4 v[180:181], off
	s_waitcnt lgkmcnt(4)
	v_mfma_f32_32x32x16_bf16 v[16:31], a[0:3], a[12:15], v[16:31]
	v_mfma_f32_32x32x16_bf16 v[0:15], a[4:7], a[12:15], v[0:15]
	s_nop 0
	s_nop 0
	s_nop 0
	s_nop 0
	s_waitcnt lgkmcnt(1)
	v_mfma_f32_32x32x16_bf16 v[48:63], a[16:19], a[24:27], v[48:63]
	v_mfma_f32_32x32x16_bf16 v[32:47], a[20:23], a[24:27], v[32:47]
	s_waitcnt vmcnt(6)
	s_waitcnt lgkmcnt(0)
	s_barrier
	ds_read_b128 a[12:15], v82 offset:53248
	ds_read_b128 a[8:11], v82 offset:49152
	ds_read_b128 a[4:7], v90
	ds_read_b128 a[0:3], v92
	s_nop 0
	v_lshl_add_u64 v[160:161], v[68:69], 0, s[28:29]
	s_nop 0
	v_mfma_f32_32x32x16_bf16 v[16:31], a[16:19], a[28:31], v[16:31]
	s_nop 0
	v_lshl_add_u64 v[162:163], v[70:71], 0, s[28:29]
	s_nop 0
	v_cmp_eq_u32_e64 s[0:1], 0, v79
	s_nop 0
	v_lshl_add_u64 v[164:165], v[72:73], 0, s[28:29]
	s_nop 0
	v_mfma_f32_32x32x16_bf16 v[0:15], a[20:23], a[28:31], v[0:15]
	s_and_b32 m0, s32, 7
	s_lshl_b32 m0, m0, 12
	s_add_i32 m0, m0, 0x0
	s_nop 0
	global_load_lds_dwordx4 v[158:159], off
	s_nop 0
	v_lshl_add_u64 v[166:167], v[74:75], 0, s[28:29]
	s_nop 0
	v_readlane_b32 s20, v215, 52
	s_nop 0
	v_lshl_add_u64 v[168:169], v[76:77], 0, s[28:29]
	s_nop 0
	v_readlane_b32 s21, v215, 53
	s_nop 0
	s_nop 0
	s_nop 0
	s_nop 0
	s_nop 0
	ds_read_b128 a[16:19], v93
	ds_read_b128 a[20:23], v91
	ds_read_b128 a[24:27], v84 offset:49152
	ds_read_b128 a[28:31], v84 offset:53248
	s_waitcnt lgkmcnt(4)
	v_mfma_f32_32x32x16_bf16 v[48:63], a[0:3], a[8:11], v[48:63]
	s_mov_b32 s23, 0
	v_mfma_f32_32x32x16_bf16 v[32:47], a[4:7], a[8:11], v[32:47]
	s_and_b32 m0, s32, 7
	s_lshl_b32 m0, m0, 12
	s_add_i32 m0, m0, 0x400
	s_nop 0
	global_load_lds_dwordx4 v[160:161], off
	v_mfma_f32_32x32x16_bf16 v[16:31], a[0:3], a[12:15], v[16:31]
	v_mfma_f32_32x32x16_bf16 v[0:15], a[4:7], a[12:15], v[0:15]
	s_and_b32 m0, s32, 7
	s_lshl_b32 m0, m0, 12
	s_add_i32 m0, m0, 0x800
	s_nop 0
	global_load_lds_dwordx4 v[162:163], off
	s_nop 0
	s_nop 0
	s_nop 0
	s_nop 0
	ds_read_b128 a[0:3], v95
	ds_read_b128 a[4:7], v94
	ds_read_b128 a[8:11], v86 offset:49152
	ds_read_b128 a[12:15], v86 offset:53248
	s_waitcnt lgkmcnt(5)
	v_mfma_f32_32x32x16_bf16 v[48:63], a[16:19], a[24:27], v[48:63]
	v_mfma_f32_32x32x16_bf16 v[32:47], a[20:23], a[24:27], v[32:47]
	s_and_b32 m0, s32, 7
	s_lshl_b32 m0, m0, 12
	s_add_i32 m0, m0, 0xc00
	s_nop 0
	global_load_lds_dwordx4 v[164:165], off
	s_waitcnt lgkmcnt(4)
	v_mfma_f32_32x32x16_bf16 v[16:31], a[16:19], a[28:31], v[16:31]
	v_mfma_f32_32x32x16_bf16 v[0:15], a[20:23], a[28:31], v[0:15]
	s_and_b32 m0, s32, 7
	s_lshl_b32 m0, m0, 11
	s_add_i32 m0, m0, 0x8000
	s_nop 0
	global_load_lds_dwordx4 v[166:167], off
	s_nop 0
	s_nop 0
	s_nop 0
	s_nop 0
	ds_read_b128 a[16:19], v97
	ds_read_b128 a[20:23], v96
	ds_read_b128 a[24:27], v88 offset:49152
	ds_read_b128 a[28:31], v88 offset:53248
	s_waitcnt lgkmcnt(5)
	v_mfma_f32_32x32x16_bf16 v[48:63], a[0:3], a[8:11], v[48:63]
	v_mfma_f32_32x32x16_bf16 v[32:47], a[4:7], a[8:11], v[32:47]
	s_and_b32 m0, s32, 7
	s_lshl_b32 m0, m0, 11
	s_add_i32 m0, m0, 0x8400
	s_nop 0
	global_load_lds_dwordx4 v[168:169], off
	s_waitcnt lgkmcnt(4)
	v_mfma_f32_32x32x16_bf16 v[16:31], a[0:3], a[12:15], v[16:31]
	v_mfma_f32_32x32x16_bf16 v[0:15], a[4:7], a[12:15], v[0:15]
	s_nop 0
	s_nop 0
	s_nop 0
	s_nop 0
	s_waitcnt lgkmcnt(1)
	v_mfma_f32_32x32x16_bf16 v[48:63], a[16:19], a[24:27], v[48:63]
	v_mfma_f32_32x32x16_bf16 v[32:47], a[20:23], a[24:27], v[32:47]
	s_waitcnt vmcnt(6)
	s_waitcnt lgkmcnt(0)
	s_barrier
	ds_read_b128 a[12:15], v101
	ds_read_b128 a[8:11], v100
	ds_read_b128 a[4:7], v99
	ds_read_b128 a[0:3], v98
	v_mfma_f32_32x32x16_bf16 v[16:31], a[16:19], a[28:31], v[16:31]
	v_mfma_f32_32x32x16_bf16 v[0:15], a[20:23], a[28:31], v[0:15]
	s_nop 0
	s_nop 0
	s_nop 0
	s_nop 0
	ds_read_b128 a[16:19], v102
	ds_read_b128 a[20:23], v103
	ds_read_b128 a[24:27], v104
	ds_read_b128 a[28:31], v105
	s_waitcnt lgkmcnt(4)
	v_mfma_f32_32x32x16_bf16 v[48:63], a[0:3], a[8:11], v[48:63]
	v_mfma_f32_32x32x16_bf16 v[32:47], a[4:7], a[8:11], v[32:47]
	v_mfma_f32_32x32x16_bf16 v[16:31], a[0:3], a[12:15], v[16:31]
	v_mfma_f32_32x32x16_bf16 v[0:15], a[4:7], a[12:15], v[0:15]
	s_nop 0
	s_nop 0
	s_nop 0
	s_nop 0
	ds_read_b128 a[0:3], v106
	ds_read_b128 a[4:7], v107
	ds_read_b128 a[8:11], v108
	ds_read_b128 a[12:15], v109
	s_waitcnt lgkmcnt(5)
	v_mfma_f32_32x32x16_bf16 v[48:63], a[16:19], a[24:27], v[48:63]
	v_mfma_f32_32x32x16_bf16 v[32:47], a[20:23], a[24:27], v[32:47]
	s_waitcnt lgkmcnt(4)
	v_mfma_f32_32x32x16_bf16 v[16:31], a[16:19], a[28:31], v[16:31]
	v_mfma_f32_32x32x16_bf16 v[0:15], a[20:23], a[28:31], v[0:15]
	s_nop 0
	s_nop 0
	s_nop 0
	s_nop 0
	ds_read_b128 a[16:19], v110
	ds_read_b128 a[20:23], v111
	ds_read_b128 a[24:27], v112
	ds_read_b128 a[28:31], v113
	s_waitcnt lgkmcnt(5)
	v_mfma_f32_32x32x16_bf16 v[48:63], a[0:3], a[8:11], v[48:63]
	v_mfma_f32_32x32x16_bf16 v[32:47], a[4:7], a[8:11], v[32:47]
	s_waitcnt lgkmcnt(4)
	v_mfma_f32_32x32x16_bf16 v[16:31], a[0:3], a[12:15], v[16:31]
	v_mfma_f32_32x32x16_bf16 v[0:15], a[4:7], a[12:15], v[0:15]
	s_nop 0
	s_nop 0
	s_nop 0
	s_nop 0
	s_waitcnt lgkmcnt(1)
	v_mfma_f32_32x32x16_bf16 v[48:63], a[16:19], a[24:27], v[48:63]
	v_mfma_f32_32x32x16_bf16 v[32:47], a[20:23], a[24:27], v[32:47]
	s_waitcnt vmcnt(0)
	s_waitcnt lgkmcnt(0)
	s_barrier
	ds_read_b128 a[12:15], v82 offset:4096
	ds_read_b128 a[8:11], v82
	ds_read_b128 a[4:7], v83 offset:36864
	ds_read_b128 a[0:3], v83 offset:32768
	v_mfma_f32_32x32x16_bf16 v[16:31], a[16:19], a[28:31], v[16:31]
	v_mfma_f32_32x32x16_bf16 v[0:15], a[20:23], a[28:31], v[0:15]
	s_nop 0
	s_nop 0
	s_nop 0
	s_nop 0
	ds_read_b128 a[16:19], v85 offset:32768
	ds_read_b128 a[20:23], v85 offset:36864
	ds_read_b128 a[24:27], v84
	ds_read_b128 a[28:31], v84 offset:4096
	s_waitcnt lgkmcnt(4)
	v_mfma_f32_32x32x16_bf16 v[48:63], a[0:3], a[8:11], v[48:63]
	v_mfma_f32_32x32x16_bf16 v[32:47], a[4:7], a[8:11], v[32:47]
	v_mfma_f32_32x32x16_bf16 v[16:31], a[0:3], a[12:15], v[16:31]
	v_mfma_f32_32x32x16_bf16 v[0:15], a[4:7], a[12:15], v[0:15]
	s_nop 0
	s_nop 0
	s_nop 0
	s_nop 0
	ds_read_b128 a[0:3], v87 offset:32768
	ds_read_b128 a[4:7], v87 offset:36864
	ds_read_b128 a[8:11], v86
	ds_read_b128 a[12:15], v86 offset:4096
	s_waitcnt lgkmcnt(5)
	v_mfma_f32_32x32x16_bf16 v[48:63], a[16:19], a[24:27], v[48:63]
	v_mfma_f32_32x32x16_bf16 v[32:47], a[20:23], a[24:27], v[32:47]
	s_waitcnt lgkmcnt(4)
	v_mfma_f32_32x32x16_bf16 v[16:31], a[16:19], a[28:31], v[16:31]
	v_mfma_f32_32x32x16_bf16 v[0:15], a[20:23], a[28:31], v[0:15]
	s_nop 0
	s_nop 0
	s_nop 0
	s_waitcnt lgkmcnt(1)
	v_mfma_f32_32x32x16_bf16 v[48:63], a[0:3], a[8:11], v[48:63]
	v_mfma_f32_32x32x16_bf16 v[32:47], a[4:7], a[8:11], v[32:47]
	s_nop 0
	s_waitcnt lgkmcnt(0)
	v_mfma_f32_32x32x16_bf16 v[0:15], a[4:7], a[12:15], v[0:15]
	v_mfma_f32_32x32x16_bf16 v[16:31], a[0:3], a[12:15], v[16:31]
	ds_read_b128 v[66:69], v89 offset:32768
	ds_read_b128 v[70:73], v88
	ds_read_b128 v[74:77], v89 offset:36864
	ds_read_b128 v[82:85], v88 offset:4096
	s_waitcnt lgkmcnt(0)
	s_barrier
	s_waitcnt lgkmcnt(0)
	v_mfma_f32_32x32x16_bf16 v[48:63], v[66:69], v[70:73], v[48:63]
	v_mfma_f32_32x32x16_bf16 v[32:47], v[74:77], v[70:73], v[32:47]
	s_nop 10
	ds_write_b128 v64, v[48:51]
	ds_write_b128 v64, v[52:55] offset:32
	ds_write_b128 v64, v[56:59] offset:64
	ds_write_b128 v64, v[60:63] offset:96
	ds_write_b128 v64, v[32:35] offset:128
	v_mfma_f32_32x32x16_bf16 v[0:15], v[74:77], v[82:85], v[0:15]
	v_mfma_f32_32x32x16_bf16 v[16:31], v[66:69], v[82:85], v[16:31]
	ds_write_b128 v64, v[36:39] offset:160
	ds_write_b128 v64, v[40:43] offset:192
	ds_write_b128 v64, v[44:47] offset:224
	s_nop 8
	ds_write_b128 v64, v[16:19] offset:16896
	ds_write_b128 v64, v[20:23] offset:16928
	ds_write_b128 v64, v[24:27] offset:16960
	ds_write_b128 v64, v[28:31] offset:16992
	ds_write_b128 v64, v[0:3] offset:17024
	ds_write_b128 v64, v[4:7] offset:17056
	ds_write_b128 v64, v[8:11] offset:17088
	ds_write_b128 v64, v[12:15] offset:17120
	s_waitcnt lgkmcnt(0)
	s_barrier
	v_lshl_or_b32 v0, v79, 2, s31
	v_ashrrev_i32_e32 v1, 31, v0
	v_lshl_add_u32 v4, v79, 4, 0
	v_lshl_add_u64 v[6:7], v[0:1], 2, s[92:93]
	v_lshl_add_u64 v[8:9], v[0:1], 1, s[20:21]
	s_branch .LBB0_161
